# s5 sub-block loops: MFMA-result pad 32 wait states -> 4 (hazard needs 8 incl. following MFMAs); diff-attention: dk-1 temporary computed only on the diagonal-tile path
# speedup vs baseline: 1.0027x; 1.0027x over previous
; #define LAS __attribute__((address_space(3)))
; __device__ __forceinline__ unsigned cvtpk(float lo, float hi) { typedef __bf16 bf2 __attribute__((ext_vector_type(2))); f32x2 v = {lo, hi}; bf2 b = __builtin_convertvector(v, bf2); return __builtin_bit_cast(unsigned, b); }
; template <int DIR, bool PASS2>
; __device__ __forceinline__ void s5_sub(LAS unsigned char* ulds, const bf16x8 (&bb)[8], const bf16x8 (&bc)[4], float lbr, float lbi, float& sr, float& si, f32x4& yacc, int sub, int lane) {
;     ...
;     u32x4 uw = {0u, 0u, 0u, 0u};
;     if (kq < 2) uw = *(const LAS u32x4*)(ulds + (sub * 16 + hq) * 32 + kq * 16);
;     const bf16x8 ua = __builtin_bit_cast(bf16x8, uw);
;     LAS float* xp = xlds + (4 * kq) * S5_XP + hq;
;     f32x4 xs[8];
; #pragma unroll
;     for (int nt = 0; nt < 8; ++nt) xs[nt] = __builtin_amdgcn_mfma_f32_16x16x32_bf16(ua, bb[nt], (f32x4){0.f, 0.f, 0.f, 0.f}, 0, 0, 0);
;     asm volatile("s_nop 15\n\ts_nop 15" : "+v"(xs[0]), "+v"(xs[1]), "+v"(xs[2]), "+v"(xs[3]), "+v"(xs[4]), "+v"(xs[5]), "+v"(xs[6]), "+v"(xs[7]));
; #pragma unroll
;     for (int nt = 0; nt < 8; ++nt) { xp[16 * nt] = xs[nt][0]; xp[16 * nt + S5_XP] = xs[nt][1]; xp[16 * nt + 2 * S5_XP] = xs[nt][2]; xp[16 * nt + 3 * S5_XP] = xs[nt][3]; }
;     asm volatile("s_waitcnt lgkmcnt(0)" ::: "memory");
;     const LAS float* xr = xlds + 2 * lane; LAS unsigned char* sw = slds + lane * 4;
; #pragma unroll
;     for (int q = 0; q < 16; ++q) {
;         const int jj = DIR ? 15 - q : q;
;         const f32x2 x = *(const LAS f32x2*)(xr + jj * S5_XP);
;         const float nr = lbr * sr - lbi * si + x[0], ni = lbr * si + lbi * sr + x[1]; sr = nr; si = ni;
;         if (PASS2) *(LAS unsigned*)(sw + jj * 272) = cvtpk(sr, si);
;     }
.LBB0_275:
	s_or_b64 exec, exec, s[10:11]
	s_waitcnt lgkmcnt(0)
	v_mfma_f32_16x16x32_bf16 v[78:81], v[34:37], v[2:5], 0
	v_add_u32_e32 v65, 0x1000, v39
	v_mfma_f32_16x16x32_bf16 v[82:85], v[34:37], v[6:9], 0
	v_mfma_f32_16x16x32_bf16 v[86:89], v[34:37], v[10:13], 0
	v_mfma_f32_16x16x32_bf16 v[90:93], v[34:37], v[14:17], 0
	v_mfma_f32_16x16x32_bf16 v[94:97], v[34:37], v[18:21], 0
	v_mfma_f32_16x16x32_bf16 v[98:101], v[34:37], v[22:25], 0
	v_mfma_f32_16x16x32_bf16 v[102:105], v[34:37], v[26:29], 0
	v_mfma_f32_16x16x32_bf16 v[34:37], v[34:37], v[30:33], 0
	s_nop 3
	s_nop 1
	ds_write2_b32 v65, v78, v82 offset1:16
	ds_write2_b32 v65, v79, v83 offset0:132 offset1:148
	v_add_u32_e32 v78, 0x1400, v39
	ds_write2_b32 v78, v80, v84 offset0:8 offset1:24
	ds_write2_b32 v78, v81, v85 offset0:140 offset1:156
	ds_write2_b32 v65, v86, v90 offset0:32 offset1:48
	ds_write2_b32 v65, v87, v91 offset0:164 offset1:180
	ds_write2_b32 v78, v88, v92 offset0:40 offset1:56
	ds_write2_b32 v78, v89, v93 offset0:172 offset1:188
	ds_write2_b32 v65, v94, v98 offset0:64 offset1:80
	ds_write2_b32 v65, v95, v99 offset0:196 offset1:212
	ds_write2_b32 v78, v96, v100 offset0:72 offset1:88
	ds_write2_b32 v78, v97, v101 offset0:204 offset1:220
	ds_write2_b32 v65, v102, v34 offset0:96 offset1:112
	ds_write2_b32 v65, v103, v35 offset0:228 offset1:244
	ds_write2_b32 v78, v104, v36 offset0:104 offset1:120
	ds_write2_b32 v78, v105, v37 offset0:236 offset1:252
	v_add_u32_e32 v82, s27, v40
	s_waitcnt lgkmcnt(0)
	v_add_u32_e32 v83, 0x2800, v82
	ds_read2_b64 v[34:37], v83 offset0:156 offset1:222
	v_pk_mul_f32 v[78:79], v[60:61], v[70:71] op_sel_hi:[1,0]
	v_add_u32_e32 v84, 0x1000, v82
	v_pk_fma_f32 v[80:81], v[62:63], v[64:65], v[78:79] neg_lo:[0,0,1] neg_hi:[0,0,1]
	v_pk_fma_f32 v[64:65], v[62:63], v[64:65], v[78:79] op_sel_hi:[1,0,1]
	s_nop 0
	v_mov_b32_e32 v81, v65
	s_waitcnt lgkmcnt(0)
	v_pk_add_f32 v[36:37], v[80:81], v[36:37]
	ds_read2_b64 v[78:81], v83 offset0:24 offset1:90
	v_mul_f32_e32 v64, v63, v37
	v_pk_fma_f32 v[64:65], v[62:63], v[36:37], v[64:65] op_sel_hi:[1,1,0] neg_lo:[0,0,1] neg_hi:[0,0,1]
	v_pk_mul_f32 v[36:37], v[60:61], v[36:37]
	v_pk_add_f32 v[64:65], v[34:35], v[64:65]
	v_add_f32_e32 v36, v37, v36
	v_pk_add_f32 v[34:35], v[34:35], v[36:37] op_sel:[1,0] op_sel_hi:[1,0]
	v_add_u32_e32 v83, 0x2000, v82
	v_pk_mul_f32 v[34:35], v[60:61], v[34:35]
	s_nop 0
	v_pk_fma_f32 v[36:37], v[62:63], v[64:65], v[34:35] neg_lo:[0,0,1] neg_hi:[0,0,1]
	v_pk_fma_f32 v[34:35], v[62:63], v[64:65], v[34:35] op_sel_hi:[1,0,1]
	s_nop 0
	v_mov_b32_e32 v37, v35
	s_waitcnt lgkmcnt(0)
	v_pk_add_f32 v[34:35], v[80:81], v[36:37]
	s_nop 0
	v_mul_f32_e32 v36, v63, v35
	v_pk_fma_f32 v[36:37], v[62:63], v[34:35], v[36:37] op_sel_hi:[1,1,0] neg_lo:[0,0,1] neg_hi:[0,0,1]
	v_pk_mul_f32 v[80:81], v[60:61], v[34:35]
	v_pk_add_f32 v[64:65], v[78:79], v[36:37]
	ds_read2_b64 v[34:37], v83 offset0:148 offset1:214
	v_add_f32_e32 v70, v81, v80
	v_pk_add_f32 v[78:79], v[78:79], v[70:71] op_sel:[1,0] op_sel_hi:[1,0]
	s_nop 0
	v_pk_mul_f32 v[78:79], v[60:61], v[78:79]
	s_nop 0
	v_pk_fma_f32 v[80:81], v[62:63], v[64:65], v[78:79] neg_lo:[0,0,1] neg_hi:[0,0,1]
	v_pk_fma_f32 v[64:65], v[62:63], v[64:65], v[78:79] op_sel_hi:[1,0,1]
	s_nop 0
	v_mov_b32_e32 v81, v65
	s_waitcnt lgkmcnt(0)
; #define LAS __attribute__((address_space(3)))
; __device__ __forceinline__ unsigned cvtpk(float lo, float hi) { typedef __bf16 bf2 __attribute__((ext_vector_type(2))); f32x2 v = {lo, hi}; bf2 b = __builtin_convertvector(v, bf2); return __builtin_bit_cast(unsigned, b); }
; template <int DIR, bool PASS2>
; __device__ __forceinline__ void s5_sub(LAS unsigned char* ulds, const bf16x8 (&bb)[8], const bf16x8 (&bc)[4], float lbr, float lbi, float& sr, float& si, f32x4& yacc, int sub, int lane) {
;     ...
;     const LAS float* xr = xlds + 2 * lane; LAS unsigned char* sw = slds + lane * 4;
; #pragma unroll
;     for (int q = 0; q < 16; ++q) {
;         const int jj = DIR ? 15 - q : q;
;         const f32x2 x = *(const LAS f32x2*)(xr + jj * S5_XP);
;         const float nr = lbr * sr - lbi * si + x[0], ni = lbr * si + lbi * sr + x[1]; sr = nr; si = ni;
;         if (PASS2) *(LAS unsigned*)(sw + jj * 272) = cvtpk(sr, si);
;     }
; template <int DIR, bool PASS2>
; __device__ __forceinline__ void s5_dir(LAS unsigned char* ulds, const bf16x8 (&bb)[8], const bf16x8 (&bc)[4], float lbr, float lbi, float& sr, float& si, f32x4 (&yacc)[8], int lane) {
;     ...
;         for (int sb = 0; sb < 8; ++sb) { const int sub = DIR ? 7 - sb : sb; s5_sub<DIR, false>(ulds, bb, bc, lbr, lbi, sr, si, yacc[0], sub, lane); }
	v_pk_add_f32 v[36:37], v[36:37], v[80:81]
	ds_read2_b64 v[78:81], v83 offset0:16 offset1:82
	v_mul_f32_e32 v64, v63, v37
	v_pk_fma_f32 v[64:65], v[62:63], v[36:37], v[64:65] op_sel_hi:[1,1,0] neg_lo:[0,0,1] neg_hi:[0,0,1]
	v_pk_mul_f32 v[36:37], v[60:61], v[36:37]
	v_pk_add_f32 v[64:65], v[34:35], v[64:65]
	v_add_f32_e32 v36, v37, v36
	v_pk_add_f32 v[34:35], v[34:35], v[36:37] op_sel:[1,0] op_sel_hi:[1,0]
	v_add_u32_e32 v83, 0x1800, v82
	v_pk_mul_f32 v[34:35], v[60:61], v[34:35]
	s_nop 0
	v_pk_fma_f32 v[36:37], v[62:63], v[64:65], v[34:35] neg_lo:[0,0,1] neg_hi:[0,0,1]
	v_pk_fma_f32 v[34:35], v[62:63], v[64:65], v[34:35] op_sel_hi:[1,0,1]
	s_nop 0
	v_mov_b32_e32 v37, v35
	s_waitcnt lgkmcnt(0)
	v_pk_add_f32 v[34:35], v[80:81], v[36:37]
	s_nop 0
	v_pk_mul_f32 v[80:81], v[60:61], v[34:35]
	v_pk_mul_f32 v[64:65], v[62:63], v[34:35]
	ds_read2_b64 v[34:37], v83 offset0:140 offset1:206
	v_add_f32_e32 v70, v81, v80
	v_pk_add_f32 v[80:81], v[78:79], v[70:71] op_sel:[1,0] op_sel_hi:[1,0]
	v_sub_f32_e32 v64, v64, v65
	v_pk_mul_f32 v[80:81], v[60:61], v[80:81]
	v_add_f32_e32 v64, v78, v64
	v_pk_fma_f32 v[78:79], v[62:63], v[64:65], v[80:81] op_sel_hi:[1,0,1]
	v_pk_fma_f32 v[64:65], v[62:63], v[64:65], v[80:81] op_sel_hi:[1,0,1] neg_lo:[0,0,1] neg_hi:[0,0,1]
	s_nop 0
	v_mov_b32_e32 v65, v79
	s_waitcnt lgkmcnt(0)
	v_pk_add_f32 v[36:37], v[36:37], v[64:65]
	ds_read2_b64 v[78:81], v83 offset0:8 offset1:74
	v_pk_mul_f32 v[64:65], v[62:63], v[36:37]
	v_pk_mul_f32 v[36:37], v[60:61], v[36:37]
	s_nop 0
	v_add_f32_e32 v36, v37, v36
	v_pk_add_f32 v[36:37], v[34:35], v[36:37] op_sel:[1,0] op_sel_hi:[1,0]
	v_sub_f32_e32 v35, v64, v65
	v_pk_mul_f32 v[36:37], v[60:61], v[36:37]
	v_add_f32_e32 v34, v34, v35
	v_pk_fma_f32 v[64:65], v[62:63], v[34:35], v[36:37] op_sel_hi:[1,0,1]
	v_pk_fma_f32 v[34:35], v[62:63], v[34:35], v[36:37] op_sel_hi:[1,0,1] neg_lo:[0,0,1] neg_hi:[0,0,1]
	s_nop 0
	v_mov_b32_e32 v35, v65
	s_waitcnt lgkmcnt(0)
	v_pk_add_f32 v[34:35], v[80:81], v[34:35]
	s_nop 0
	v_mul_f32_e32 v36, v63, v35
	v_pk_fma_f32 v[36:37], v[62:63], v[34:35], v[36:37] op_sel_hi:[1,1,0] neg_lo:[0,0,1] neg_hi:[0,0,1]
	v_pk_mul_f32 v[80:81], v[60:61], v[34:35]
	v_pk_add_f32 v[64:65], v[78:79], v[36:37]
	ds_read2_b64 v[34:37], v84 offset0:132 offset1:198
	v_add_f32_e32 v70, v81, v80
	v_pk_add_f32 v[78:79], v[78:79], v[70:71] op_sel:[1,0] op_sel_hi:[1,0]
	s_nop 0
	v_pk_mul_f32 v[78:79], v[60:61], v[78:79]
	s_nop 0
	v_pk_fma_f32 v[82:83], v[62:63], v[64:65], v[78:79] neg_lo:[0,0,1] neg_hi:[0,0,1]
	v_pk_fma_f32 v[64:65], v[62:63], v[64:65], v[78:79] op_sel_hi:[1,0,1]
	ds_read2_b64 v[78:81], v84 offset1:66
	v_mov_b32_e32 v83, v65
	s_waitcnt lgkmcnt(1)
	v_pk_add_f32 v[36:37], v[36:37], v[82:83]
	s_waitcnt lgkmcnt(0)
	s_nop 0
	v_pk_mul_f32 v[64:65], v[68:69], v[36:37]
	s_nop 0
	v_pk_fma_f32 v[82:83], v[66:67], v[36:37], v[64:65] op_sel:[0,0,1] op_sel_hi:[1,1,0] neg_lo:[0,0,1] neg_hi:[0,0,1]
	v_pk_fma_f32 v[36:37], v[66:67], v[36:37], v[64:65] op_sel:[0,0,1] op_sel_hi:[1,1,0]
	s_nop 0
	v_mov_b32_e32 v83, v37
	v_pk_add_f32 v[34:35], v[34:35], v[82:83]
	s_nop 0
	v_pk_mul_f32 v[36:37], v[68:69], v[34:35]
	s_nop 0
	v_pk_fma_f32 v[64:65], v[66:67], v[34:35], v[36:37] op_sel:[0,0,1] op_sel_hi:[1,1,0] neg_lo:[0,0,1] neg_hi:[0,0,1]
	v_pk_fma_f32 v[34:35], v[66:67], v[34:35], v[36:37] op_sel:[0,0,1] op_sel_hi:[1,1,0]
	s_nop 0
	v_mov_b32_e32 v65, v35
	s_waitcnt lgkmcnt(0)
	v_pk_add_f32 v[34:35], v[80:81], v[64:65]
	s_nop 0
	v_pk_mul_f32 v[36:37], v[68:69], v[34:35]
	s_nop 0
	v_pk_fma_f32 v[64:65], v[66:67], v[34:35], v[36:37] op_sel:[0,0,1] op_sel_hi:[1,1,0] neg_lo:[0,0,1] neg_hi:[0,0,1]
	v_pk_fma_f32 v[34:35], v[66:67], v[34:35], v[36:37] op_sel:[0,0,1] op_sel_hi:[1,1,0]
	s_nop 0
	v_mov_b32_e32 v65, v35
	v_pk_add_f32 v[64:65], v[78:79], v[64:65]
	s_addk_i32 s42, 0xfe00
	s_cmpk_lg_i32 s42, 0xfe00
	v_mov_b32_e32 v70, v65
	s_cbranch_scc0 .LBB0_278

; #define LAS __attribute__((address_space(3)))
; __device__ __forceinline__ unsigned cvtpk(float lo, float hi) { typedef __bf16 bf2 __attribute__((ext_vector_type(2))); f32x2 v = {lo, hi}; bf2 b = __builtin_convertvector(v, bf2); return __builtin_bit_cast(unsigned, b); }
; template <int DIR, bool PASS2>
; __device__ __forceinline__ void s5_sub(LAS unsigned char* ulds, const bf16x8 (&bb)[8], const bf16x8 (&bc)[4], float lbr, float lbi, float& sr, float& si, f32x4& yacc, int sub, int lane) {
;     ...
;     u32x4 uw = {0u, 0u, 0u, 0u};
;     if (kq < 2) uw = *(const LAS u32x4*)(ulds + (sub * 16 + hq) * 32 + kq * 16);
;     const bf16x8 ua = __builtin_bit_cast(bf16x8, uw);
;     LAS float* xp = xlds + (4 * kq) * S5_XP + hq;
;     f32x4 xs[8];
; #pragma unroll
;     for (int nt = 0; nt < 8; ++nt) xs[nt] = __builtin_amdgcn_mfma_f32_16x16x32_bf16(ua, bb[nt], (f32x4){0.f, 0.f, 0.f, 0.f}, 0, 0, 0);
;     asm volatile("s_nop 15\n\ts_nop 15" : "+v"(xs[0]), "+v"(xs[1]), "+v"(xs[2]), "+v"(xs[3]), "+v"(xs[4]), "+v"(xs[5]), "+v"(xs[6]), "+v"(xs[7]));
; #pragma unroll
;     for (int nt = 0; nt < 8; ++nt) { xp[16 * nt] = xs[nt][0]; xp[16 * nt + S5_XP] = xs[nt][1]; xp[16 * nt + 2 * S5_XP] = xs[nt][2]; xp[16 * nt + 3 * S5_XP] = xs[nt][3]; }
;     asm volatile("s_waitcnt lgkmcnt(0)" ::: "memory");
;     const LAS float* xr = xlds + 2 * lane; LAS unsigned char* sw = slds + lane * 4;
; #pragma unroll
;     for (int q = 0; q < 16; ++q) {
;         const int jj = DIR ? 15 - q : q;
;         const f32x2 x = *(const LAS f32x2*)(xr + jj * S5_XP);
;         const float nr = lbr * sr - lbi * si + x[0], ni = lbr * si + lbi * sr + x[1]; sr = nr; si = ni;
;         if (PASS2) *(LAS unsigned*)(sw + jj * 272) = cvtpk(sr, si);
;     }
.LBB0_281:
	s_or_b64 exec, exec, s[10:11]
	s_waitcnt lgkmcnt(0)
	v_mfma_f32_16x16x32_bf16 v[78:81], v[34:37], v[2:5], 0
	v_add_u32_e32 v70, 0x1000, v39
	v_mfma_f32_16x16x32_bf16 v[82:85], v[34:37], v[6:9], 0
	v_mfma_f32_16x16x32_bf16 v[86:89], v[34:37], v[10:13], 0
	v_mfma_f32_16x16x32_bf16 v[90:93], v[34:37], v[14:17], 0
	v_mfma_f32_16x16x32_bf16 v[94:97], v[34:37], v[18:21], 0
	v_mfma_f32_16x16x32_bf16 v[98:101], v[34:37], v[22:25], 0
	v_mfma_f32_16x16x32_bf16 v[102:105], v[34:37], v[26:29], 0
	v_mfma_f32_16x16x32_bf16 v[34:37], v[34:37], v[30:33], 0
	s_nop 3
	s_nop 1
	ds_write2_b32 v70, v78, v82 offset1:16
	ds_write2_b32 v70, v79, v83 offset0:132 offset1:148
	v_add_u32_e32 v78, 0x1400, v39
	ds_write2_b32 v78, v80, v84 offset0:8 offset1:24
	ds_write2_b32 v78, v81, v85 offset0:140 offset1:156
	ds_write2_b32 v70, v86, v90 offset0:32 offset1:48
	ds_write2_b32 v70, v87, v91 offset0:164 offset1:180
	ds_write2_b32 v78, v88, v92 offset0:40 offset1:56
	ds_write2_b32 v78, v89, v93 offset0:172 offset1:188
	ds_write2_b32 v70, v94, v98 offset0:64 offset1:80
	ds_write2_b32 v70, v95, v99 offset0:196 offset1:212
	ds_write2_b32 v78, v96, v100 offset0:72 offset1:88
	ds_write2_b32 v78, v97, v101 offset0:204 offset1:220
	ds_write2_b32 v70, v102, v34 offset0:96 offset1:112
	ds_write2_b32 v70, v103, v35 offset0:228 offset1:244
	ds_write2_b32 v78, v104, v36 offset0:104 offset1:120
	ds_write2_b32 v78, v105, v37 offset0:236 offset1:252
	v_add_u32_e32 v86, s27, v40
	s_waitcnt lgkmcnt(0)
	v_add_u32_e32 v80, 0x1000, v86
	ds_read2_b64 v[34:37], v80 offset1:66
	v_mul_f32_e32 v70, v63, v65
	v_pk_fma_f32 v[78:79], v[62:63], v[64:65], v[70:71] op_sel_hi:[1,1,0] neg_lo:[0,0,1] neg_hi:[0,0,1]
	v_pk_mul_f32 v[64:65], v[60:61], v[64:65]
	v_add_u32_e32 v70, 0x1800, v86
	v_add_f32_e32 v64, v64, v65
	s_waitcnt lgkmcnt(0)
	v_pk_add_f32 v[78:79], v[78:79], v[34:35]
	v_pk_add_f32 v[34:35], v[64:65], v[34:35] op_sel:[0,1] op_sel_hi:[0,1]
	v_pk_mul_f32 v[34:35], v[60:61], v[34:35]
	ds_read2_b64 v[82:85], v70 offset0:8 offset1:74
	v_pk_fma_f32 v[64:65], v[62:63], v[78:79], v[34:35] neg_lo:[0,0,1] neg_hi:[0,0,1]
	v_pk_fma_f32 v[34:35], v[62:63], v[78:79], v[34:35] op_sel_hi:[1,0,1]
	ds_read2_b64 v[78:81], v80 offset0:132 offset1:198
	v_mov_b32_e32 v65, v35
	v_pk_add_f32 v[34:35], v[36:37], v[64:65]
	s_nop 0
	v_pk_mul_f32 v[36:37], v[68:69], v[34:35]
	s_nop 0
	v_pk_fma_f32 v[64:65], v[66:67], v[34:35], v[36:37] op_sel:[0,0,1] op_sel_hi:[1,1,0]
	v_pk_fma_f32 v[34:35], v[66:67], v[34:35], v[36:37] op_sel:[0,0,1] op_sel_hi:[1,1,0] neg_lo:[0,0,1] neg_hi:[0,0,1]
	s_nop 0
	v_mov_b32_e32 v35, v65
	s_waitcnt lgkmcnt(0)
	v_pk_add_f32 v[34:35], v[78:79], v[34:35]
	s_nop 0
	v_pk_mul_f32 v[36:37], v[68:69], v[34:35]
	s_nop 0
	v_pk_fma_f32 v[64:65], v[66:67], v[34:35], v[36:37] op_sel:[0,0,1] op_sel_hi:[1,1,0]
	v_pk_fma_f32 v[34:35], v[66:67], v[34:35], v[36:37] op_sel:[0,0,1] op_sel_hi:[1,1,0] neg_lo:[0,0,1] neg_hi:[0,0,1]
	s_nop 0
	v_mov_b32_e32 v35, v65
	v_pk_add_f32 v[34:35], v[80:81], v[34:35]
	s_nop 0
	v_pk_mul_f32 v[36:37], v[68:69], v[34:35]
	s_nop 0
	v_pk_fma_f32 v[64:65], v[66:67], v[34:35], v[36:37] op_sel:[0,0,1] op_sel_hi:[1,1,0]
	v_pk_fma_f32 v[34:35], v[66:67], v[34:35], v[36:37] op_sel:[0,0,1] op_sel_hi:[1,1,0] neg_lo:[0,0,1] neg_hi:[0,0,1]
	s_nop 0
	v_mov_b32_e32 v35, v65
	v_pk_add_f32 v[34:35], v[82:83], v[34:35]
	s_nop 0
	v_mul_f32_e32 v36, v63, v35
	v_pk_fma_f32 v[64:65], v[62:63], v[34:35], v[36:37] op_sel_hi:[1,1,0] neg_lo:[0,0,1] neg_hi:[0,0,1]
	v_mul_f32_e32 v36, v60, v34
	v_pk_fma_f32 v[82:83], v[60:61], v[34:35], v[36:37] op_sel_hi:[1,1,0]
	ds_read2_b64 v[34:37], v70 offset0:140 offset1:206
	v_mov_b32_e32 v65, v83
	v_pk_add_f32 v[64:65], v[84:85], v[64:65]
	v_add_u32_e32 v70, 0x2000, v86
	v_pk_mul_f32 v[82:83], v[68:69], v[64:65]
	ds_read2_b64 v[78:81], v70 offset0:16 offset1:82
	v_pk_fma_f32 v[84:85], v[66:67], v[64:65], v[82:83] op_sel:[0,0,1] op_sel_hi:[1,1,0] neg_lo:[0,0,1] neg_hi:[0,0,1]
	v_pk_fma_f32 v[64:65], v[66:67], v[64:65], v[82:83] op_sel:[0,0,1] op_sel_hi:[1,1,0]
	s_nop 0
	v_mov_b32_e32 v85, v65
	s_waitcnt lgkmcnt(1)
; #define LAS __attribute__((address_space(3)))
; __device__ __forceinline__ unsigned cvtpk(float lo, float hi) { typedef __bf16 bf2 __attribute__((ext_vector_type(2))); f32x2 v = {lo, hi}; bf2 b = __builtin_convertvector(v, bf2); return __builtin_bit_cast(unsigned, b); }
; template <int DIR, bool PASS2>
; __device__ __forceinline__ void s5_sub(LAS unsigned char* ulds, const bf16x8 (&bb)[8], const bf16x8 (&bc)[4], float lbr, float lbi, float& sr, float& si, f32x4& yacc, int sub, int lane) {
;     ...
;     const LAS float* xr = xlds + 2 * lane; LAS unsigned char* sw = slds + lane * 4;
; #pragma unroll
;     for (int q = 0; q < 16; ++q) {
;         const int jj = DIR ? 15 - q : q;
;         const f32x2 x = *(const LAS f32x2*)(xr + jj * S5_XP);
;         const float nr = lbr * sr - lbi * si + x[0], ni = lbr * si + lbi * sr + x[1]; sr = nr; si = ni;
;         if (PASS2) *(LAS unsigned*)(sw + jj * 272) = cvtpk(sr, si);
;     }
; template <int DIR, bool PASS2>
; __device__ __forceinline__ void s5_dir(LAS unsigned char* ulds, const bf16x8 (&bb)[8], const bf16x8 (&bc)[4], float lbr, float lbi, float& sr, float& si, f32x4 (&yacc)[8], int lane) {
;     ...
;         for (int sb = 0; sb < 8; ++sb) { const int sub = DIR ? 7 - sb : sb; s5_sub<DIR, false>(ulds, bb, bc, lbr, lbi, sr, si, yacc[0], sub, lane); }
	v_pk_add_f32 v[34:35], v[34:35], v[84:85]
	s_nop 0
	v_pk_mul_f32 v[64:65], v[68:69], v[34:35]
	s_nop 0
	v_pk_fma_f32 v[82:83], v[66:67], v[34:35], v[64:65] op_sel:[0,0,1] op_sel_hi:[1,1,0] neg_lo:[0,0,1] neg_hi:[0,0,1]
	v_pk_fma_f32 v[34:35], v[66:67], v[34:35], v[64:65] op_sel:[0,0,1] op_sel_hi:[1,1,0]
	s_nop 0
	v_mov_b32_e32 v83, v35
	v_pk_add_f32 v[34:35], v[36:37], v[82:83]
	s_nop 0
	v_pk_mul_f32 v[36:37], v[68:69], v[34:35]
	s_nop 0
	v_pk_fma_f32 v[64:65], v[66:67], v[34:35], v[36:37] op_sel:[0,0,1] op_sel_hi:[1,1,0] neg_lo:[0,0,1] neg_hi:[0,0,1]
	v_pk_fma_f32 v[34:35], v[66:67], v[34:35], v[36:37] op_sel:[0,0,1] op_sel_hi:[1,1,0]
	s_nop 0
	v_mov_b32_e32 v65, v35
	s_waitcnt lgkmcnt(0)
	v_pk_add_f32 v[64:65], v[78:79], v[64:65]
	ds_read2_b64 v[34:37], v70 offset0:148 offset1:214
	v_pk_mul_f32 v[78:79], v[68:69], v[64:65]
	v_add_u32_e32 v70, 0x2800, v86
	v_pk_fma_f32 v[86:87], v[66:67], v[64:65], v[78:79] op_sel:[0,0,1] op_sel_hi:[1,1,0] neg_lo:[0,0,1] neg_hi:[0,0,1]
	v_pk_fma_f32 v[64:65], v[66:67], v[64:65], v[78:79] op_sel:[0,0,1] op_sel_hi:[1,1,0]
	ds_read2_b64 v[82:85], v70 offset0:24 offset1:90
	v_mov_b32_e32 v87, v65
	v_pk_add_f32 v[64:65], v[80:81], v[86:87]
	s_nop 0
	v_pk_mul_f32 v[78:79], v[68:69], v[64:65]
	s_nop 0
	v_pk_fma_f32 v[80:81], v[66:67], v[64:65], v[78:79] op_sel:[0,0,1] op_sel_hi:[1,1,0] neg_lo:[0,0,1] neg_hi:[0,0,1]
	v_pk_fma_f32 v[64:65], v[66:67], v[64:65], v[78:79] op_sel:[0,0,1] op_sel_hi:[1,1,0]
	s_nop 0
	v_mov_b32_e32 v81, v65
	s_waitcnt lgkmcnt(1)
	v_pk_add_f32 v[34:35], v[34:35], v[80:81]
	s_nop 0
	v_pk_mul_f32 v[64:65], v[68:69], v[34:35]
	s_nop 0
	v_pk_fma_f32 v[78:79], v[66:67], v[34:35], v[64:65] op_sel:[0,0,1] op_sel_hi:[1,1,0] neg_lo:[0,0,1] neg_hi:[0,0,1]
	v_pk_fma_f32 v[34:35], v[66:67], v[34:35], v[64:65] op_sel:[0,0,1] op_sel_hi:[1,1,0]
	s_nop 0
	v_mov_b32_e32 v79, v35
	v_pk_add_f32 v[34:35], v[36:37], v[78:79]
	s_nop 0
	v_pk_mul_f32 v[36:37], v[68:69], v[34:35]
	s_nop 0
	v_pk_fma_f32 v[64:65], v[66:67], v[34:35], v[36:37] op_sel:[0,0,1] op_sel_hi:[1,1,0] neg_lo:[0,0,1] neg_hi:[0,0,1]
	v_pk_fma_f32 v[34:35], v[66:67], v[34:35], v[36:37] op_sel:[0,0,1] op_sel_hi:[1,1,0]
	s_nop 0
	v_mov_b32_e32 v65, v35
	s_waitcnt lgkmcnt(0)
	v_pk_add_f32 v[64:65], v[82:83], v[64:65]
	ds_read2_b64 v[34:37], v70 offset0:156 offset1:222
	v_pk_mul_f32 v[78:79], v[68:69], v[64:65]
	s_waitcnt lgkmcnt(0)
	s_nop 0
	v_pk_fma_f32 v[80:81], v[66:67], v[64:65], v[78:79] op_sel:[0,0,1] op_sel_hi:[1,1,0] neg_lo:[0,0,1] neg_hi:[0,0,1]
	v_pk_fma_f32 v[64:65], v[66:67], v[64:65], v[78:79] op_sel:[0,0,1] op_sel_hi:[1,1,0]
	s_nop 0
	v_mov_b32_e32 v81, v65
	v_pk_add_f32 v[64:65], v[84:85], v[80:81]
	s_nop 0
	v_pk_mul_f32 v[78:79], v[68:69], v[64:65]
	s_nop 0
	v_pk_fma_f32 v[80:81], v[66:67], v[64:65], v[78:79] op_sel:[0,0,1] op_sel_hi:[1,1,0] neg_lo:[0,0,1] neg_hi:[0,0,1]
	v_pk_fma_f32 v[64:65], v[66:67], v[64:65], v[78:79] op_sel:[0,0,1] op_sel_hi:[1,1,0]
	s_nop 0
	v_mov_b32_e32 v81, v65
	s_waitcnt lgkmcnt(0)
	v_pk_add_f32 v[34:35], v[34:35], v[80:81]
	s_nop 0
	v_pk_mul_f32 v[64:65], v[68:69], v[34:35]
	s_nop 0
	v_pk_fma_f32 v[78:79], v[66:67], v[34:35], v[64:65] op_sel:[0,0,1] op_sel_hi:[1,1,0] neg_lo:[0,0,1] neg_hi:[0,0,1]
	v_pk_fma_f32 v[34:35], v[66:67], v[34:35], v[64:65] op_sel:[0,0,1] op_sel_hi:[1,1,0]
	s_nop 0
	v_mov_b32_e32 v79, v35
	v_pk_add_f32 v[64:65], v[36:37], v[78:79]
	s_addk_i32 s42, 0x200
	s_cmpk_eq_i32 s42, 0x1000
	s_cbranch_scc1 .LBB0_270

; #define LAS __attribute__((address_space(3)))
; template <int DIR, bool PASS2>
; __device__ __forceinline__ void s5_sub(LAS unsigned char* ulds, const bf16x8 (&bb)[8], const bf16x8 (&bc)[4], float lbr, float lbi, float& sr, float& si, f32x4& yacc, int sub, int lane) {
;     ...
;     u32x4 uw = {0u, 0u, 0u, 0u};
;     if (kq < 2) uw = *(const LAS u32x4*)(ulds + (sub * 16 + hq) * 32 + kq * 16);
;     const bf16x8 ua = __builtin_bit_cast(bf16x8, uw);
;     LAS float* xp = xlds + (4 * kq) * S5_XP + hq;
;     f32x4 xs[8];
; #pragma unroll
;     for (int nt = 0; nt < 8; ++nt) xs[nt] = __builtin_amdgcn_mfma_f32_16x16x32_bf16(ua, bb[nt], (f32x4){0.f, 0.f, 0.f, 0.f}, 0, 0, 0);
;     asm volatile("s_nop 15\n\ts_nop 15" : "+v"(xs[0]), "+v"(xs[1]), "+v"(xs[2]), "+v"(xs[3]), "+v"(xs[4]), "+v"(xs[5]), "+v"(xs[6]), "+v"(xs[7]));
; #pragma unroll
;     for (int nt = 0; nt < 8; ++nt) { xp[16 * nt] = xs[nt][0]; xp[16 * nt + S5_XP] = xs[nt][1]; xp[16 * nt + 2 * S5_XP] = xs[nt][2]; xp[16 * nt + 3 * S5_XP] = xs[nt][3]; }
;     asm volatile("s_waitcnt lgkmcnt(0)" ::: "memory");
;     const LAS float* xr = xlds + 2 * lane; LAS unsigned char* sw = slds + lane * 4;
; #pragma unroll
;     for (int q = 0; q < 16; ++q) {
;         const int jj = DIR ? 15 - q : q;
;         const f32x2 x = *(const LAS f32x2*)(xr + jj * S5_XP);
;         const float nr = lbr * sr - lbi * si + x[0], ni = lbr * si + lbi * sr + x[1]; sr = nr; si = ni;
;         if (PASS2) *(LAS unsigned*)(sw + jj * 272) = cvtpk(sr, si);
;     }
;     if (PASS2) {
;         asm volatile("s_waitcnt lgkmcnt(0)" ::: "memory");
;         f32x4 acc = DIR ? yacc : (f32x4){0.f, 0.f, 0.f, 0.f};
;         const LAS unsigned char* sa = slds + hq * 272 + kq * 16;
; #pragma unroll
;         for (int ks = 0; ks < 4; ++ks) { const bf16x8 a = *(const LAS bf16x8*)(sa + ks * 64); acc = __builtin_amdgcn_mfma_f32_16x16x32_bf16(a, bc[ks], acc, 0, 0, 0); }
; __device__ __forceinline__ void s5h_pass2(PPtr P, int li, LAS unsigned char* lds, int gw, int NGW, int wave, int lane) {
;     ...
;                 bf16_t* drow = dst + (size_t)(sub * 16 + 4 * kq) * LDP;
;                 float yf[4] = {0.f, 0.f, 0.f, 0.f};
;                 if (dir) {
; #pragma unroll
;                     for (int i = 0; i < 4; ++i) yf[i] = bf1(drow[(size_t)i * LDP]);
;                 }
.LBB0_493:
	s_and_b64 s[10:11], s[50:51], exec
	s_cselect_b32 s10, s38, s68
	v_lshl_or_b32 v64, s10, 4, v78
	v_mul_lo_u32 v68, v64, s70
	v_cndmask_b32_e64 v50, 0, 1, s[64:65]
	v_lshl_add_u64 v[56:57], v[68:69], 1, v[96:97]
	v_cmp_ne_u32_e64 s[10:11], 1, v50
	s_andn2_b64 vcc, exec, s[64:65]
	s_mov_b64 s[66:67], -1
	s_cbranch_vccnz .LBB0_499
	v_add_co_u32_e32 v50, vcc, 0x1000, v56
	s_nop 1
	v_addc_co_u32_e32 v51, vcc, 0, v57, vcc
	v_add_co_u32_e32 v52, vcc, 0x3000, v56
	s_nop 1
	v_addc_co_u32_e32 v53, vcc, 0, v57, vcc
	v_add_co_u32_e32 v62, vcc, 0x4000, v56
	s_nop 1
	v_addc_co_u32_e32 v63, vcc, 0, v57, vcc
	global_load_ushort v60, v[56:57], off
	global_load_ushort v58, v[50:51], off offset:2368
	global_load_ushort v59, v[52:53], off offset:640
	global_load_ushort v65, v[62:63], off offset:3008
	v_mov_b32_e32 v50, 0
	v_mov_b32_e32 v51, 0
	v_mov_b32_e32 v52, 0
	v_mov_b32_e32 v53, 0
	s_and_saveexec_b64 s[66:67], s[8:9]
	ds_read_b128 v[50:53], v93
	s_or_b64 exec, exec, s[66:67]
	s_waitcnt lgkmcnt(0)
	v_mfma_f32_16x16x32_bf16 v[110:113], v[50:53], v[2:5], 0
	v_add_u32_e32 v61, v67, v73
	v_add_u32_e32 v62, 0x1000, v61
	v_add_u32_e32 v61, 0x1400, v61
	v_mfma_f32_16x16x32_bf16 v[128:131], v[50:53], v[6:9], 0
	v_mul_f32_e32 v68, v105, v106
	v_add_u32_e32 v114, s27, v77
	v_mfma_f32_16x16x32_bf16 v[132:135], v[50:53], v[10:13], 0
	v_mfma_f32_16x16x32_bf16 v[136:139], v[50:53], v[14:17], 0
	v_mfma_f32_16x16x32_bf16 v[140:143], v[50:53], v[18:21], 0
	v_mfma_f32_16x16x32_bf16 v[144:147], v[50:53], v[22:25], 0
	v_mfma_f32_16x16x32_bf16 v[148:151], v[50:53], v[26:29], 0
	v_mfma_f32_16x16x32_bf16 v[50:53], v[50:53], v[30:33], 0
	s_nop 3
	ds_write2_b32 v62, v110, v128 offset1:16
	ds_write2_b32 v62, v111, v129 offset0:132 offset1:148
	ds_write2_b32 v61, v112, v130 offset0:8 offset1:24
	ds_write2_b32 v61, v113, v131 offset0:140 offset1:156
	ds_write2_b32 v62, v132, v136 offset0:32 offset1:48
	ds_write2_b32 v62, v133, v137 offset0:164 offset1:180
	ds_write2_b32 v61, v134, v138 offset0:40 offset1:56
	ds_write2_b32 v61, v135, v139 offset0:172 offset1:188
	ds_write2_b32 v62, v140, v144 offset0:64 offset1:80
	ds_write2_b32 v62, v141, v145 offset0:196 offset1:212
	ds_write2_b32 v61, v142, v146 offset0:72 offset1:88
	ds_write2_b32 v61, v143, v147 offset0:204 offset1:220
	ds_write2_b32 v62, v148, v50 offset0:96 offset1:112
	ds_write2_b32 v62, v149, v51 offset0:228 offset1:244
	ds_write2_b32 v61, v150, v52 offset0:104 offset1:120
	ds_write2_b32 v61, v151, v53 offset0:236 offset1:252
	v_add_u32_e32 v61, s27, v72
	s_waitcnt lgkmcnt(0)
	v_add_u32_e32 v109, 0x2800, v61
	ds_read2_b64 v[50:53], v109 offset0:156 offset1:222
	v_mul_f32_e32 v62, v105, v107
	v_pk_fma_f32 v[62:63], v[104:105], v[106:107], v[62:63] op_sel_hi:[1,1,0] neg_lo:[0,0,1] neg_hi:[0,0,1]
	v_pk_fma_f32 v[110:111], v[104:105], v[106:107], v[68:69] op_sel:[0,1,0] op_sel_hi:[1,0,0]
	v_add_u32_e32 v115, 0x2000, v61
	s_waitcnt lgkmcnt(0)
	v_pk_add_f32 v[62:63], v[62:63], v[52:53]
	v_pk_add_f32 v[52:53], v[110:111], v[52:53] op_sel:[0,1] op_sel_hi:[1,0]
	s_nop 0
	v_mov_b32_e32 v63, v52
	v_mul_f32_e32 v68, v105, v52
	v_cvt_pk_bf16_f32 v112, v62, v52
	v_pk_fma_f32 v[110:111], v[104:105], v[62:63], v[68:69] op_sel_hi:[1,1,0] neg_lo:[0,0,1] neg_hi:[0,0,1]
	v_mov_b32_e32 v53, v62
	v_mul_f32_e32 v62, v105, v62
	v_pk_fma_f32 v[52:53], v[104:105], v[52:53], v[62:63] op_sel_hi:[1,1,0]
	v_pk_add_f32 v[110:111], v[50:51], v[110:111]
	v_pk_add_f32 v[62:63], v[50:51], v[52:53] op_sel:[1,0] op_sel_hi:[0,1]
	ds_read2_b64 v[50:53], v109 offset0:24 offset1:90
	v_cvt_pk_bf16_f32 v63, v110, v62
	v_add_u32_e32 v68, 0x3e00, v114
	v_mov_b32_e32 v111, v62
	ds_write2_b32 v68, v63, v112 offset0:120 offset1:188
	v_mul_f32_e32 v68, v105, v62
	v_pk_fma_f32 v[112:113], v[104:105], v[110:111], v[68:69] op_sel_hi:[1,1,0] neg_lo:[0,0,1] neg_hi:[0,0,1]
	v_mov_b32_e32 v63, v110
	v_mul_f32_e32 v68, v105, v110
	v_pk_fma_f32 v[62:63], v[104:105], v[62:63], v[68:69] op_sel_hi:[1,1,0]
	s_waitcnt lgkmcnt(1)
	v_pk_add_f32 v[112:113], v[52:53], v[112:113]
	v_pk_add_f32 v[52:53], v[52:53], v[62:63] op_sel:[1,0] op_sel_hi:[0,1]
	v_mov_b32_e32 v113, v52
	v_mul_f32_e32 v62, v105, v52
	v_mov_b32_e32 v53, v112
	v_mul_f32_e32 v68, v105, v112
	v_cvt_pk_bf16_f32 v109, v112, v52
	v_pk_fma_f32 v[62:63], v[104:105], v[112:113], v[62:63] op_sel_hi:[1,1,0] neg_lo:[0,0,1] neg_hi:[0,0,1]
	v_pk_fma_f32 v[52:53], v[104:105], v[52:53], v[68:69] op_sel_hi:[1,1,0]
	v_pk_add_f32 v[62:63], v[50:51], v[62:63]
	v_pk_add_f32 v[110:111], v[50:51], v[52:53] op_sel:[1,0] op_sel_hi:[0,1]
	ds_read2_b64 v[50:53], v115 offset0:148 offset1:214
	v_cvt_pk_bf16_f32 v68, v62, v110
	v_add_u32_e32 v111, 0x3c00, v114
	v_mov_b32_e32 v63, v110
	ds_write2_b32 v111, v68, v109 offset0:112 offset1:180
	v_mul_f32_e32 v68, v105, v110
	v_pk_fma_f32 v[112:113], v[104:105], v[62:63], v[68:69] op_sel_hi:[1,1,0] neg_lo:[0,0,1] neg_hi:[0,0,1]
	v_mov_b32_e32 v111, v62
	v_mul_f32_e32 v62, v105, v62
	v_pk_fma_f32 v[62:63], v[104:105], v[110:111], v[62:63] op_sel_hi:[1,1,0]
	s_waitcnt lgkmcnt(1)
	v_pk_add_f32 v[112:113], v[52:53], v[112:113]
	v_pk_add_f32 v[52:53], v[52:53], v[62:63] op_sel:[1,0] op_sel_hi:[0,1]
	v_mov_b32_e32 v113, v52
	v_mul_f32_e32 v62, v105, v52
	v_mov_b32_e32 v53, v112
	v_mul_f32_e32 v68, v105, v112
	v_cvt_pk_bf16_f32 v109, v112, v52
	v_pk_fma_f32 v[62:63], v[104:105], v[112:113], v[62:63] op_sel_hi:[1,1,0] neg_lo:[0,0,1] neg_hi:[0,0,1]
	v_pk_fma_f32 v[52:53], v[104:105], v[52:53], v[68:69] op_sel_hi:[1,1,0]
	v_pk_add_f32 v[62:63], v[50:51], v[62:63]
	v_pk_add_f32 v[110:111], v[50:51], v[52:53] op_sel:[1,0] op_sel_hi:[0,1]
	ds_read2_b64 v[50:53], v115 offset0:16 offset1:82
	v_cvt_pk_bf16_f32 v68, v62, v110
	v_add_u32_e32 v111, 0x3a00, v114
	v_mov_b32_e32 v63, v110
	ds_write2_b32 v111, v68, v109 offset0:104 offset1:172
	v_mul_f32_e32 v68, v105, v110
	v_pk_fma_f32 v[112:113], v[104:105], v[62:63], v[68:69] op_sel_hi:[1,1,0] neg_lo:[0,0,1] neg_hi:[0,0,1]
	v_mov_b32_e32 v111, v62
	v_mul_f32_e32 v62, v105, v62
	v_pk_fma_f32 v[62:63], v[104:105], v[110:111], v[62:63] op_sel_hi:[1,1,0]
	s_waitcnt lgkmcnt(1)
; #define LAS __attribute__((address_space(3)))
; __device__ __forceinline__ unsigned cvtpk(float lo, float hi) { typedef __bf16 bf2 __attribute__((ext_vector_type(2))); f32x2 v = {lo, hi}; bf2 b = __builtin_convertvector(v, bf2); return __builtin_bit_cast(unsigned, b); }
; template <int DIR, bool PASS2>
; __device__ __forceinline__ void s5_sub(LAS unsigned char* ulds, const bf16x8 (&bb)[8], const bf16x8 (&bc)[4], float lbr, float lbi, float& sr, float& si, f32x4& yacc, int sub, int lane) {
;     ...
;     const LAS float* xr = xlds + 2 * lane; LAS unsigned char* sw = slds + lane * 4;
; #pragma unroll
;     for (int q = 0; q < 16; ++q) {
;         const int jj = DIR ? 15 - q : q;
;         const f32x2 x = *(const LAS f32x2*)(xr + jj * S5_XP);
;         const float nr = lbr * sr - lbi * si + x[0], ni = lbr * si + lbi * sr + x[1]; sr = nr; si = ni;
;         if (PASS2) *(LAS unsigned*)(sw + jj * 272) = cvtpk(sr, si);
;     }
;     if (PASS2) {
;         asm volatile("s_waitcnt lgkmcnt(0)" ::: "memory");
;         f32x4 acc = DIR ? yacc : (f32x4){0.f, 0.f, 0.f, 0.f};
;         const LAS unsigned char* sa = slds + hq * 272 + kq * 16;
; #pragma unroll
;         for (int ks = 0; ks < 4; ++ks) { const bf16x8 a = *(const LAS bf16x8*)(sa + ks * 64); acc = __builtin_amdgcn_mfma_f32_16x16x32_bf16(a, bc[ks], acc, 0, 0, 0); }
;         yacc = acc;
	v_pk_add_f32 v[112:113], v[52:53], v[112:113]
	v_pk_add_f32 v[52:53], v[52:53], v[62:63] op_sel:[1,0] op_sel_hi:[0,1]
	v_mov_b32_e32 v113, v52
	v_mul_f32_e32 v62, v105, v52
	v_mov_b32_e32 v53, v112
	v_mul_f32_e32 v68, v105, v112
	v_cvt_pk_bf16_f32 v109, v112, v52
	v_pk_fma_f32 v[62:63], v[104:105], v[112:113], v[62:63] op_sel_hi:[1,1,0] neg_lo:[0,0,1] neg_hi:[0,0,1]
	v_pk_fma_f32 v[52:53], v[104:105], v[52:53], v[68:69] op_sel_hi:[1,1,0]
	v_add_u32_e32 v115, 0x1800, v61
	v_pk_add_f32 v[62:63], v[50:51], v[62:63]
	v_pk_add_f32 v[110:111], v[50:51], v[52:53] op_sel:[1,0] op_sel_hi:[0,1]
	ds_read2_b64 v[50:53], v115 offset0:140 offset1:206
	v_cvt_pk_bf16_f32 v68, v62, v110
	v_add_u32_e32 v111, 0x3800, v114
	v_mov_b32_e32 v63, v110
	ds_write2_b32 v111, v68, v109 offset0:96 offset1:164
	v_mul_f32_e32 v68, v105, v110
	v_pk_fma_f32 v[112:113], v[104:105], v[62:63], v[68:69] op_sel_hi:[1,1,0] neg_lo:[0,0,1] neg_hi:[0,0,1]
	v_mov_b32_e32 v111, v62
	v_mul_f32_e32 v62, v105, v62
	v_pk_fma_f32 v[62:63], v[104:105], v[110:111], v[62:63] op_sel_hi:[1,1,0]
	s_waitcnt lgkmcnt(1)
	v_pk_add_f32 v[112:113], v[52:53], v[112:113]
	v_pk_add_f32 v[52:53], v[52:53], v[62:63] op_sel:[1,0] op_sel_hi:[0,1]
	v_mov_b32_e32 v113, v52
	v_mul_f32_e32 v62, v105, v52
	v_mov_b32_e32 v53, v112
	v_mul_f32_e32 v68, v105, v112
	v_cvt_pk_bf16_f32 v109, v112, v52
	v_pk_fma_f32 v[62:63], v[104:105], v[112:113], v[62:63] op_sel_hi:[1,1,0] neg_lo:[0,0,1] neg_hi:[0,0,1]
	v_pk_fma_f32 v[52:53], v[104:105], v[52:53], v[68:69] op_sel_hi:[1,1,0]
	v_pk_add_f32 v[62:63], v[50:51], v[62:63]
	v_pk_add_f32 v[110:111], v[50:51], v[52:53] op_sel:[1,0] op_sel_hi:[0,1]
	ds_read2_b64 v[50:53], v115 offset0:8 offset1:74
	v_cvt_pk_bf16_f32 v68, v62, v110
	v_add_u32_e32 v111, 0x3600, v114
	v_mov_b32_e32 v63, v110
	ds_write2_b32 v111, v68, v109 offset0:88 offset1:156
	v_mul_f32_e32 v68, v105, v110
	v_pk_fma_f32 v[112:113], v[104:105], v[62:63], v[68:69] op_sel_hi:[1,1,0] neg_lo:[0,0,1] neg_hi:[0,0,1]
	v_mov_b32_e32 v111, v62
	v_mul_f32_e32 v62, v105, v62
	v_pk_fma_f32 v[62:63], v[104:105], v[110:111], v[62:63] op_sel_hi:[1,1,0]
	s_waitcnt lgkmcnt(1)
	v_pk_add_f32 v[112:113], v[52:53], v[112:113]
	v_pk_add_f32 v[52:53], v[52:53], v[62:63] op_sel:[1,0] op_sel_hi:[0,1]
	v_mov_b32_e32 v113, v52
	v_mul_f32_e32 v62, v105, v52
	v_mov_b32_e32 v53, v112
	v_mul_f32_e32 v68, v105, v112
	v_cvt_pk_bf16_f32 v109, v112, v52
	v_pk_fma_f32 v[62:63], v[104:105], v[112:113], v[62:63] op_sel_hi:[1,1,0] neg_lo:[0,0,1] neg_hi:[0,0,1]
	v_pk_fma_f32 v[52:53], v[104:105], v[52:53], v[68:69] op_sel_hi:[1,1,0]
	v_add_u32_e32 v61, 0x1000, v61
	v_pk_add_f32 v[62:63], v[50:51], v[62:63]
	v_pk_add_f32 v[110:111], v[50:51], v[52:53] op_sel:[1,0] op_sel_hi:[0,1]
	ds_read2_b64 v[50:53], v61 offset0:132 offset1:198
	v_cvt_pk_bf16_f32 v68, v62, v110
	v_add_u32_e32 v111, 0x3400, v114
	v_mov_b32_e32 v63, v110
	ds_write2_b32 v111, v68, v109 offset0:80 offset1:148
	v_mul_f32_e32 v68, v105, v110
	v_pk_fma_f32 v[112:113], v[104:105], v[62:63], v[68:69] op_sel_hi:[1,1,0] neg_lo:[0,0,1] neg_hi:[0,0,1]
	v_mov_b32_e32 v111, v62
	v_mul_f32_e32 v62, v105, v62
	v_pk_fma_f32 v[62:63], v[104:105], v[110:111], v[62:63] op_sel_hi:[1,1,0]
	s_waitcnt lgkmcnt(1)
	v_pk_add_f32 v[112:113], v[52:53], v[112:113]
	v_pk_add_f32 v[52:53], v[52:53], v[62:63] op_sel:[1,0] op_sel_hi:[0,1]
	v_mov_b32_e32 v113, v52
	v_mul_f32_e32 v62, v105, v52
	v_mov_b32_e32 v53, v112
	v_mul_f32_e32 v68, v105, v112
	v_cvt_pk_bf16_f32 v109, v112, v52
	v_pk_fma_f32 v[62:63], v[104:105], v[112:113], v[62:63] op_sel_hi:[1,1,0] neg_lo:[0,0,1] neg_hi:[0,0,1]
	v_pk_fma_f32 v[52:53], v[104:105], v[52:53], v[68:69] op_sel_hi:[1,1,0]
	v_pk_add_f32 v[62:63], v[50:51], v[62:63]
	v_pk_add_f32 v[110:111], v[50:51], v[52:53] op_sel:[1,0] op_sel_hi:[0,1]
	v_cvt_pk_bf16_f32 v50, v62, v110
	v_add_u32_e32 v51, 0x3200, v114
	ds_write2_b32 v51, v50, v109 offset0:72 offset1:140
	ds_read2_b64 v[50:53], v61 offset1:66
	v_mov_b32_e32 v63, v110
	v_pk_mul_f32 v[112:113], v[104:105], v[62:63]
	v_mov_b32_e32 v111, v62
	v_mul_f32_e32 v62, v105, v62
	v_pk_fma_f32 v[62:63], v[104:105], v[110:111], v[62:63] op_sel_hi:[1,1,0]
	s_waitcnt lgkmcnt(0)
	v_pk_add_f32 v[62:63], v[52:53], v[62:63] op_sel:[1,0] op_sel_hi:[0,1]
	v_sub_f32_e32 v53, v112, v113
	v_add_f32_e32 v52, v52, v53
	v_cvt_pk_bf16_f32 v61, v52, v62
	v_pk_mul_f32 v[62:63], v[54:55], v[62:63] op_sel_hi:[1,0]
	s_nop 0
	v_pk_fma_f32 v[110:111], v[104:105], v[52:53], v[62:63] op_sel_hi:[1,0,1] neg_lo:[0,0,1] neg_hi:[0,0,1]
	v_pk_fma_f32 v[52:53], v[104:105], v[52:53], v[62:63] op_sel_hi:[1,0,1]
	s_nop 0
	v_mov_b32_e32 v111, v53
	v_pk_add_f32 v[62:63], v[50:51], v[110:111]
	v_add_u32_e32 v51, 0x3000, v114
	v_cvt_pk_bf16_f32 v50, v62, v63
	ds_write2_b32 v51, v50, v61 offset0:64 offset1:132
	s_waitcnt lgkmcnt(0)
	v_add_u32_e32 v61, v79, v116
	ds_read_b128 v[50:53], v61 offset:12544
	ds_read_b128 v[110:113], v61 offset:12608
	s_waitcnt lgkmcnt(1)
	v_mfma_f32_16x16x32_bf16 v[50:53], v[50:53], v[34:37], 0
	ds_read_b128 v[128:131], v61 offset:12672
	s_waitcnt lgkmcnt(1)
	v_mfma_f32_16x16x32_bf16 v[50:53], v[110:113], v[38:41], v[50:53]
	ds_read_b128 v[110:113], v61 offset:12736
	s_waitcnt lgkmcnt(0)
	s_waitcnt vmcnt(3)
	v_lshlrev_b32_e32 v60, 16, v60
	s_waitcnt vmcnt(2)
	v_lshlrev_b32_e32 v61, 16, v58
	s_waitcnt lgkmcnt(1)
	v_mfma_f32_16x16x32_bf16 v[50:53], v[128:131], v[42:45], v[50:53]
	s_waitcnt vmcnt(1)
	v_lshlrev_b32_e32 v58, 16, v59
	s_waitcnt vmcnt(0)
	v_lshlrev_b32_e32 v59, 16, v65
	s_waitcnt lgkmcnt(0)
	v_mfma_f32_16x16x32_bf16 v[50:53], v[110:113], v[46:49], v[50:53]

; #define LAS __attribute__((address_space(3)))
; __device__ __forceinline__ unsigned cvtpk(float lo, float hi) { typedef __bf16 bf2 __attribute__((ext_vector_type(2))); f32x2 v = {lo, hi}; bf2 b = __builtin_convertvector(v, bf2); return __builtin_bit_cast(unsigned, b); }
; template <int DIR, bool PASS2>
; __device__ __forceinline__ void s5_sub(LAS unsigned char* ulds, const bf16x8 (&bb)[8], const bf16x8 (&bc)[4], float lbr, float lbi, float& sr, float& si, f32x4& yacc, int sub, int lane) {
;     ...
;     u32x4 uw = {0u, 0u, 0u, 0u};
;     if (kq < 2) uw = *(const LAS u32x4*)(ulds + (sub * 16 + hq) * 32 + kq * 16);
;     const bf16x8 ua = __builtin_bit_cast(bf16x8, uw);
;     LAS float* xp = xlds + (4 * kq) * S5_XP + hq;
;     f32x4 xs[8];
; #pragma unroll
;     for (int nt = 0; nt < 8; ++nt) xs[nt] = __builtin_amdgcn_mfma_f32_16x16x32_bf16(ua, bb[nt], (f32x4){0.f, 0.f, 0.f, 0.f}, 0, 0, 0);
;     asm volatile("s_nop 15\n\ts_nop 15" : "+v"(xs[0]), "+v"(xs[1]), "+v"(xs[2]), "+v"(xs[3]), "+v"(xs[4]), "+v"(xs[5]), "+v"(xs[6]), "+v"(xs[7]));
; #pragma unroll
;     for (int nt = 0; nt < 8; ++nt) { xp[16 * nt] = xs[nt][0]; xp[16 * nt + S5_XP] = xs[nt][1]; xp[16 * nt + 2 * S5_XP] = xs[nt][2]; xp[16 * nt + 3 * S5_XP] = xs[nt][3]; }
;     asm volatile("s_waitcnt lgkmcnt(0)" ::: "memory");
;     const LAS float* xr = xlds + 2 * lane; LAS unsigned char* sw = slds + lane * 4;
; #pragma unroll
;     for (int q = 0; q < 16; ++q) {
;         const int jj = DIR ? 15 - q : q;
;         const f32x2 x = *(const LAS f32x2*)(xr + jj * S5_XP);
;         const float nr = lbr * sr - lbi * si + x[0], ni = lbr * si + lbi * sr + x[1]; sr = nr; si = ni;
;         if (PASS2) *(LAS unsigned*)(sw + jj * 272) = cvtpk(sr, si);
;     }
;     if (PASS2) {
;         asm volatile("s_waitcnt lgkmcnt(0)" ::: "memory");
;         f32x4 acc = DIR ? yacc : (f32x4){0.f, 0.f, 0.f, 0.f};
;         const LAS unsigned char* sa = slds + hq * 272 + kq * 16;
; #pragma unroll
;         for (int ks = 0; ks < 4; ++ks) { const bf16x8 a = *(const LAS bf16x8*)(sa + ks * 64); acc = __builtin_amdgcn_mfma_f32_16x16x32_bf16(a, bc[ks], acc, 0, 0, 0); }
.LBB0_499:
	s_and_b64 vcc, exec, s[66:67]
	s_cbranch_vccz .LBB0_497
	v_mov_b32_e32 v59, 0
	v_mov_b32_e32 v50, 0
	v_mov_b32_e32 v51, 0
	v_mov_b32_e32 v52, 0
	v_mov_b32_e32 v53, 0
	s_and_saveexec_b64 s[66:67], s[8:9]
	ds_read_b128 v[50:53], v108
	s_or_b64 exec, exec, s[66:67]
	s_waitcnt lgkmcnt(0)
	v_mfma_f32_16x16x32_bf16 v[60:63], v[50:53], v[2:5], 0
	v_add_u32_e32 v58, v67, v73
	v_add_u32_e32 v65, 0x1000, v58
	v_add_u32_e32 v58, 0x1400, v58
	v_mfma_f32_16x16x32_bf16 v[110:113], v[50:53], v[6:9], 0
	v_add_u32_e32 v109, s27, v77
	v_mfma_f32_16x16x32_bf16 v[128:131], v[50:53], v[10:13], 0
	v_mfma_f32_16x16x32_bf16 v[132:135], v[50:53], v[14:17], 0
	v_mfma_f32_16x16x32_bf16 v[136:139], v[50:53], v[18:21], 0
	v_mfma_f32_16x16x32_bf16 v[140:143], v[50:53], v[22:25], 0
	v_mfma_f32_16x16x32_bf16 v[144:147], v[50:53], v[26:29], 0
	v_mfma_f32_16x16x32_bf16 v[50:53], v[50:53], v[30:33], 0
	s_nop 3
	s_nop 0
	ds_write2_b32 v65, v60, v110 offset1:16
	ds_write2_b32 v65, v61, v111 offset0:132 offset1:148
	ds_write2_b32 v58, v62, v112 offset0:8 offset1:24
	ds_write2_b32 v58, v63, v113 offset0:140 offset1:156
	ds_write2_b32 v65, v128, v132 offset0:32 offset1:48
	ds_write2_b32 v65, v129, v133 offset0:164 offset1:180
	ds_write2_b32 v58, v130, v134 offset0:40 offset1:56
	ds_write2_b32 v58, v131, v135 offset0:172 offset1:188
	ds_write2_b32 v65, v136, v140 offset0:64 offset1:80
	ds_write2_b32 v65, v137, v141 offset0:196 offset1:212
	ds_write2_b32 v58, v138, v142 offset0:72 offset1:88
	ds_write2_b32 v58, v139, v143 offset0:204 offset1:220
	ds_write2_b32 v65, v144, v50 offset0:96 offset1:112
	ds_write2_b32 v65, v145, v51 offset0:228 offset1:244
	ds_write2_b32 v58, v146, v52 offset0:104 offset1:120
	ds_write2_b32 v58, v147, v53 offset0:236 offset1:252
	v_add_u32_e32 v65, s27, v72
	s_waitcnt lgkmcnt(0)
	v_add_u32_e32 v68, 0x1000, v65
	ds_read2_b64 v[50:53], v68 offset1:66
	v_mul_f32_e32 v58, v105, v107
	v_pk_fma_f32 v[60:61], v[104:105], v[106:107], v[58:59] op_sel_hi:[1,1,0] neg_lo:[0,0,1] neg_hi:[0,0,1]
	v_mul_f32_e32 v58, v55, v107
	v_pk_fma_f32 v[62:63], v[54:55], v[106:107], v[58:59] op_sel_hi:[1,1,0]
	s_waitcnt lgkmcnt(0)
	v_pk_add_f32 v[60:61], v[60:61], v[50:51]
	v_pk_add_f32 v[50:51], v[62:63], v[50:51] op_sel:[0,1] op_sel_hi:[1,0]
	v_add_u32_e32 v110, 0x1800, v65
	v_mov_b32_e32 v61, v50
	v_mul_f32_e32 v58, v105, v50
	v_pk_fma_f32 v[62:63], v[104:105], v[60:61], v[58:59] op_sel_hi:[1,1,0] neg_lo:[0,0,1] neg_hi:[0,0,1]
	v_mov_b32_e32 v51, v60
	v_mul_f32_e32 v58, v105, v60
	v_cvt_pk_bf16_f32 v106, v60, v50
	v_pk_fma_f32 v[50:51], v[104:105], v[50:51], v[58:59] op_sel_hi:[1,1,0]
	v_pk_add_f32 v[62:63], v[52:53], v[62:63]
	v_pk_add_f32 v[60:61], v[52:53], v[50:51] op_sel:[1,0] op_sel_hi:[0,1]
	ds_read2_b64 v[50:53], v68 offset0:132 offset1:198
	v_cvt_pk_bf16_f32 v58, v62, v60
	v_add_u32_e32 v61, 0x3000, v109
	v_mov_b32_e32 v63, v60
	ds_write2_b32 v61, v106, v58 offset0:64 offset1:132
	v_mul_f32_e32 v58, v105, v60
	v_pk_fma_f32 v[106:107], v[104:105], v[62:63], v[58:59] op_sel_hi:[1,1,0] neg_lo:[0,0,1] neg_hi:[0,0,1]
	v_mov_b32_e32 v61, v62
	v_mul_f32_e32 v58, v105, v62
	v_pk_fma_f32 v[60:61], v[104:105], v[60:61], v[58:59] op_sel_hi:[1,1,0]
	s_waitcnt lgkmcnt(1)
	v_pk_add_f32 v[106:107], v[50:51], v[106:107]
	v_pk_add_f32 v[50:51], v[50:51], v[60:61] op_sel:[1,0] op_sel_hi:[0,1]
	v_mov_b32_e32 v107, v50
	v_mul_f32_e32 v58, v105, v50
	v_pk_fma_f32 v[60:61], v[104:105], v[106:107], v[58:59] op_sel_hi:[1,1,0] neg_lo:[0,0,1] neg_hi:[0,0,1]
	v_mov_b32_e32 v51, v106
	v_mul_f32_e32 v58, v105, v106
	v_cvt_pk_bf16_f32 v68, v106, v50
	v_pk_fma_f32 v[50:51], v[104:105], v[50:51], v[58:59] op_sel_hi:[1,1,0]
	v_pk_add_f32 v[60:61], v[52:53], v[60:61]
	v_pk_add_f32 v[62:63], v[52:53], v[50:51] op_sel:[1,0] op_sel_hi:[0,1]
	ds_read2_b64 v[50:53], v110 offset0:8 offset1:74
	v_cvt_pk_bf16_f32 v58, v60, v62
	v_add_u32_e32 v63, 0x3200, v109
	v_mov_b32_e32 v61, v62
	ds_write2_b32 v63, v68, v58 offset0:72 offset1:140
	v_mul_f32_e32 v58, v105, v62
	v_pk_fma_f32 v[106:107], v[104:105], v[60:61], v[58:59] op_sel_hi:[1,1,0] neg_lo:[0,0,1] neg_hi:[0,0,1]
	v_mov_b32_e32 v63, v60
	v_mul_f32_e32 v58, v105, v60
	v_pk_fma_f32 v[60:61], v[104:105], v[62:63], v[58:59] op_sel_hi:[1,1,0]
	s_waitcnt lgkmcnt(1)
	v_pk_add_f32 v[106:107], v[50:51], v[106:107]
	v_pk_add_f32 v[50:51], v[50:51], v[60:61] op_sel:[1,0] op_sel_hi:[0,1]
	v_mov_b32_e32 v107, v50
	v_mul_f32_e32 v58, v105, v50
	v_pk_fma_f32 v[60:61], v[104:105], v[106:107], v[58:59] op_sel_hi:[1,1,0] neg_lo:[0,0,1] neg_hi:[0,0,1]
	v_mov_b32_e32 v51, v106
	v_mul_f32_e32 v58, v105, v106
	v_cvt_pk_bf16_f32 v68, v106, v50
	v_pk_fma_f32 v[50:51], v[104:105], v[50:51], v[58:59] op_sel_hi:[1,1,0]
	v_pk_add_f32 v[60:61], v[52:53], v[60:61]
	v_pk_add_f32 v[62:63], v[52:53], v[50:51] op_sel:[1,0] op_sel_hi:[0,1]
	ds_read2_b64 v[50:53], v110 offset0:140 offset1:206
	v_cvt_pk_bf16_f32 v58, v60, v62
	v_add_u32_e32 v63, 0x3400, v109
	v_mov_b32_e32 v61, v62
	ds_write2_b32 v63, v68, v58 offset0:80 offset1:148
	v_mul_f32_e32 v58, v105, v62
	v_pk_fma_f32 v[106:107], v[104:105], v[60:61], v[58:59] op_sel_hi:[1,1,0] neg_lo:[0,0,1] neg_hi:[0,0,1]
	v_mov_b32_e32 v63, v60
	v_mul_f32_e32 v58, v105, v60
	v_pk_fma_f32 v[60:61], v[104:105], v[62:63], v[58:59] op_sel_hi:[1,1,0]
	s_waitcnt lgkmcnt(1)
; #define LAS __attribute__((address_space(3)))
; __device__ __forceinline__ unsigned cvtpk(float lo, float hi) { typedef __bf16 bf2 __attribute__((ext_vector_type(2))); f32x2 v = {lo, hi}; bf2 b = __builtin_convertvector(v, bf2); return __builtin_bit_cast(unsigned, b); }
; __device__ __forceinline__ bf16_t tobf(float f) { return (bf16_t)(cvtpk(f, 0.f) & 0xffffu); }
; template <int DIR, bool PASS2>
; __device__ __forceinline__ void s5_sub(LAS unsigned char* ulds, const bf16x8 (&bb)[8], const bf16x8 (&bc)[4], float lbr, float lbi, float& sr, float& si, f32x4& yacc, int sub, int lane) {
;     ...
;     const LAS float* xr = xlds + 2 * lane; LAS unsigned char* sw = slds + lane * 4;
; #pragma unroll
;     for (int q = 0; q < 16; ++q) {
;         const int jj = DIR ? 15 - q : q;
;         const f32x2 x = *(const LAS f32x2*)(xr + jj * S5_XP);
;         const float nr = lbr * sr - lbi * si + x[0], ni = lbr * si + lbi * sr + x[1]; sr = nr; si = ni;
;         if (PASS2) *(LAS unsigned*)(sw + jj * 272) = cvtpk(sr, si);
;     }
;     if (PASS2) {
;         asm volatile("s_waitcnt lgkmcnt(0)" ::: "memory");
;         f32x4 acc = DIR ? yacc : (f32x4){0.f, 0.f, 0.f, 0.f};
;         const LAS unsigned char* sa = slds + hq * 272 + kq * 16;
; #pragma unroll
;         for (int ks = 0; ks < 4; ++ks) { const bf16x8 a = *(const LAS bf16x8*)(sa + ks * 64); acc = __builtin_amdgcn_mfma_f32_16x16x32_bf16(a, bc[ks], acc, 0, 0, 0); }
;         yacc = acc;
; __device__ __forceinline__ void s5h_pass2(PPtr P, int li, LAS unsigned char* lds, int gw, int NGW, int wave, int lane) {
;     ...
;                 if (dir == 0) {
; #pragma unroll
;                     for (int i = 0; i < 4; ++i) drow[(size_t)i * LDP] = tobf(acc[i]);
	v_pk_add_f32 v[106:107], v[50:51], v[106:107]
	v_pk_add_f32 v[50:51], v[50:51], v[60:61] op_sel:[1,0] op_sel_hi:[0,1]
	v_mov_b32_e32 v107, v50
	v_mul_f32_e32 v58, v105, v50
	v_pk_fma_f32 v[60:61], v[104:105], v[106:107], v[58:59] op_sel_hi:[1,1,0] neg_lo:[0,0,1] neg_hi:[0,0,1]
	v_mov_b32_e32 v51, v106
	v_mul_f32_e32 v58, v105, v106
	v_cvt_pk_bf16_f32 v68, v106, v50
	v_pk_fma_f32 v[50:51], v[104:105], v[50:51], v[58:59] op_sel_hi:[1,1,0]
	v_add_u32_e32 v110, 0x2000, v65
	v_pk_add_f32 v[60:61], v[52:53], v[60:61]
	v_pk_add_f32 v[62:63], v[52:53], v[50:51] op_sel:[1,0] op_sel_hi:[0,1]
	ds_read2_b64 v[50:53], v110 offset0:16 offset1:82
	v_cvt_pk_bf16_f32 v58, v60, v62
	v_add_u32_e32 v63, 0x3600, v109
	v_mov_b32_e32 v61, v62
	ds_write2_b32 v63, v68, v58 offset0:88 offset1:156
	v_mul_f32_e32 v58, v105, v62
	v_pk_fma_f32 v[106:107], v[104:105], v[60:61], v[58:59] op_sel_hi:[1,1,0] neg_lo:[0,0,1] neg_hi:[0,0,1]
	v_mov_b32_e32 v63, v60
	v_mul_f32_e32 v58, v105, v60
	v_pk_fma_f32 v[60:61], v[104:105], v[62:63], v[58:59] op_sel_hi:[1,1,0]
	s_waitcnt lgkmcnt(1)
	v_pk_add_f32 v[106:107], v[50:51], v[106:107]
	v_pk_add_f32 v[50:51], v[50:51], v[60:61] op_sel:[1,0] op_sel_hi:[0,1]
	v_mov_b32_e32 v107, v50
	v_mul_f32_e32 v58, v105, v50
	v_pk_fma_f32 v[60:61], v[104:105], v[106:107], v[58:59] op_sel_hi:[1,1,0] neg_lo:[0,0,1] neg_hi:[0,0,1]
	v_mov_b32_e32 v51, v106
	v_mul_f32_e32 v58, v105, v106
	v_cvt_pk_bf16_f32 v68, v106, v50
	v_pk_fma_f32 v[50:51], v[104:105], v[50:51], v[58:59] op_sel_hi:[1,1,0]
	v_pk_add_f32 v[60:61], v[52:53], v[60:61]
	v_pk_add_f32 v[62:63], v[52:53], v[50:51] op_sel:[1,0] op_sel_hi:[0,1]
	ds_read2_b64 v[50:53], v110 offset0:148 offset1:214
	v_cvt_pk_bf16_f32 v58, v60, v62
	v_add_u32_e32 v63, 0x3800, v109
	v_mov_b32_e32 v61, v62
	ds_write2_b32 v63, v68, v58 offset0:96 offset1:164
	v_mul_f32_e32 v58, v105, v62
	v_pk_fma_f32 v[106:107], v[104:105], v[60:61], v[58:59] op_sel_hi:[1,1,0] neg_lo:[0,0,1] neg_hi:[0,0,1]
	v_mov_b32_e32 v63, v60
	v_mul_f32_e32 v58, v105, v60
	v_pk_fma_f32 v[60:61], v[104:105], v[62:63], v[58:59] op_sel_hi:[1,1,0]
	s_waitcnt lgkmcnt(1)
	v_pk_add_f32 v[106:107], v[50:51], v[106:107]
	v_pk_add_f32 v[50:51], v[50:51], v[60:61] op_sel:[1,0] op_sel_hi:[0,1]
	v_mov_b32_e32 v107, v50
	v_mul_f32_e32 v58, v105, v50
	v_pk_fma_f32 v[60:61], v[104:105], v[106:107], v[58:59] op_sel_hi:[1,1,0] neg_lo:[0,0,1] neg_hi:[0,0,1]
	v_mov_b32_e32 v51, v106
	v_mul_f32_e32 v58, v105, v106
	v_cvt_pk_bf16_f32 v68, v106, v50
	v_pk_fma_f32 v[50:51], v[104:105], v[50:51], v[58:59] op_sel_hi:[1,1,0]
	v_add_u32_e32 v65, 0x2800, v65
	v_pk_add_f32 v[60:61], v[52:53], v[60:61]
	v_pk_add_f32 v[62:63], v[52:53], v[50:51] op_sel:[1,0] op_sel_hi:[0,1]
	ds_read2_b64 v[50:53], v65 offset0:24 offset1:90
	v_cvt_pk_bf16_f32 v58, v60, v62
	v_add_u32_e32 v63, 0x3a00, v109
	v_mov_b32_e32 v61, v62
	ds_write2_b32 v63, v68, v58 offset0:104 offset1:172
	v_mul_f32_e32 v58, v105, v62
	v_pk_fma_f32 v[106:107], v[104:105], v[60:61], v[58:59] op_sel_hi:[1,1,0] neg_lo:[0,0,1] neg_hi:[0,0,1]
	v_mov_b32_e32 v63, v60
	v_mul_f32_e32 v58, v105, v60
	v_pk_fma_f32 v[60:61], v[104:105], v[62:63], v[58:59] op_sel_hi:[1,1,0]
	s_waitcnt lgkmcnt(1)
	v_pk_add_f32 v[106:107], v[50:51], v[106:107]
	v_pk_add_f32 v[50:51], v[50:51], v[60:61] op_sel:[1,0] op_sel_hi:[0,1]
	v_mov_b32_e32 v107, v50
	v_mul_f32_e32 v58, v105, v50
	v_pk_fma_f32 v[60:61], v[104:105], v[106:107], v[58:59] op_sel_hi:[1,1,0] neg_lo:[0,0,1] neg_hi:[0,0,1]
	v_mov_b32_e32 v51, v106
	v_mul_f32_e32 v58, v105, v106
	v_cvt_pk_bf16_f32 v68, v106, v50
	v_pk_fma_f32 v[50:51], v[104:105], v[50:51], v[58:59] op_sel_hi:[1,1,0]
	v_pk_add_f32 v[60:61], v[52:53], v[60:61]
	v_pk_add_f32 v[62:63], v[52:53], v[50:51] op_sel:[1,0] op_sel_hi:[0,1]
	v_cvt_pk_bf16_f32 v50, v60, v62
	v_add_u32_e32 v51, 0x3c00, v109
	ds_write2_b32 v51, v68, v50 offset0:112 offset1:180
	ds_read2_b64 v[50:53], v65 offset0:156 offset1:222
	v_mov_b32_e32 v61, v62
	v_mov_b32_e32 v63, v60
	v_mul_f32_e32 v58, v105, v60
	v_pk_mul_f32 v[106:107], v[104:105], v[60:61]
	v_pk_fma_f32 v[60:61], v[104:105], v[62:63], v[58:59] op_sel_hi:[1,1,0]
	s_waitcnt lgkmcnt(0)
	v_pk_add_f32 v[60:61], v[50:51], v[60:61] op_sel:[1,0] op_sel_hi:[0,1]
	v_sub_f32_e32 v51, v106, v107
	v_add_f32_e32 v50, v50, v51
	v_cvt_pk_bf16_f32 v58, v50, v60
	v_pk_mul_f32 v[60:61], v[54:55], v[60:61] op_sel_hi:[1,0]
	s_nop 0
	v_pk_fma_f32 v[62:63], v[104:105], v[50:51], v[60:61] op_sel_hi:[1,0,1] neg_lo:[0,0,1] neg_hi:[0,0,1]
	v_pk_fma_f32 v[50:51], v[104:105], v[50:51], v[60:61] op_sel_hi:[1,0,1]
	s_nop 0
	v_mov_b32_e32 v63, v51
	v_pk_add_f32 v[62:63], v[52:53], v[62:63]
	v_add_u32_e32 v51, 0x3e00, v109
	v_cvt_pk_bf16_f32 v50, v62, v63
	ds_write2_b32 v51, v58, v50 offset0:120 offset1:188
	s_waitcnt lgkmcnt(0)
	v_add_u32_e32 v58, v79, v116
	ds_read_b128 v[50:53], v58 offset:12544
	ds_read_b128 v[110:113], v58 offset:12608
	s_waitcnt lgkmcnt(1)
	v_mfma_f32_16x16x32_bf16 v[50:53], v[50:53], v[34:37], 0
	ds_read_b128 v[128:131], v58 offset:12672
	s_waitcnt lgkmcnt(1)
	v_mfma_f32_16x16x32_bf16 v[50:53], v[110:113], v[38:41], v[50:53]
	ds_read_b128 v[110:113], v58 offset:12736
	s_waitcnt lgkmcnt(0)
	s_waitcnt lgkmcnt(1)
	v_mfma_f32_16x16x32_bf16 v[50:53], v[128:131], v[42:45], v[50:53]
	s_waitcnt lgkmcnt(0)
	v_mfma_f32_16x16x32_bf16 v[50:53], v[110:113], v[46:49], v[50:53]
	v_mov_b32_e32 v58, 0
	v_mov_b32_e32 v61, 0
	v_mov_b32_e32 v60, 0
	v_mov_b64_e32 v[106:107], v[62:63]
	s_and_b64 vcc, exec, s[10:11]
	s_mov_b64 s[10:11], -1
	s_cbranch_vccz .LBB0_498

; #define LAS __attribute__((address_space(3)))
; template <int DQK, int DV, bool BIAS> ...
;     ...
;         const LAS unsigned char* kb = lds + buf * KBUF + r32 * KP + hi * 16;
; #pragma unroll
;         for (int ks = 0; ks < NKS; ++ks) {
;             const bf16x8 k0 = *(const LAS bf16x8*)(kb + ks * 32), k1 = *(const LAS bf16x8*)(kb + 32 * KP + ks * 32);
;             if (ks == 0) { p0 = __builtin_amdgcn_mfma_f32_32x32x16_bf16(k0, qf[0], negm, 0, 0, 0); p1 = __builtin_amdgcn_mfma_f32_32x32x16_bf16(k1, qf[0], negm, 0, 0, 0); }
;             else { p0 = __builtin_amdgcn_mfma_f32_32x32x16_bf16(k0, qf[ks], p0, 0, 0, 0); p1 = __builtin_amdgcn_mfma_f32_32x32x16_bf16(k1, qf[ks], p1, 0, 0, 0); }
;         }
;         if (BIAS) {
;             asm volatile("s_nop 15\n\ts_nop 7" : "+v"(p0), "+v"(p1));
;             const float d0 = qp - (float)(t * 64 + 4 * hi);
; #pragma unroll
;             for (int r = 0; r < 16; ++r) { const float dk = d0 - (float)((r & 3) + 8 * (r >> 2)); p0[r] = p0[r] - sl2 * fabsf(dk); p1[r] = p1[r] - sl2 * fabsf(dk - 32.f); }
.Lcb1_ok:
	ds_read_b128 v[82:85], v175
	ds_read_b128 v[152:155], v175 offset:32
	ds_read_b128 v[156:159], v175 offset:4608
	ds_read_b128 v[160:163], v175 offset:4640
	v_cvt_f32_u32_e32 v150, v173
	s_waitcnt lgkmcnt(3)
	v_mfma_f32_32x32x16_bf16 v[98:113], v[82:85], v[114:117], v[66:81]
	v_sub_f32_e32 v178, v172, v150
	s_waitcnt lgkmcnt(1)
	v_mfma_f32_32x32x16_bf16 v[82:97], v[156:159], v[114:117], v[234:249]
	v_mfma_f32_32x32x16_bf16 v[98:113], v[152:155], v[118:121], v[98:113]
	ds_read_b128 v[152:155], v175 offset:64
	ds_read_b128 v[156:159], v175 offset:96
	s_waitcnt lgkmcnt(2)
	v_mfma_f32_32x32x16_bf16 v[82:97], v[160:163], v[118:121], v[82:97]
	s_waitcnt lgkmcnt(1)
	v_mfma_f32_32x32x16_bf16 v[98:113], v[152:155], v[122:125], v[98:113]
	ds_read_b128 v[152:155], v175 offset:4672
	ds_read_b128 v[160:163], v175 offset:4704
	s_waitcnt lgkmcnt(1)
	v_mfma_f32_32x32x16_bf16 v[82:97], v[152:155], v[122:125], v[82:97]
	v_mfma_f32_32x32x16_bf16 v[98:113], v[156:159], v[126:129], v[98:113]
	s_waitcnt lgkmcnt(0)
	v_mfma_f32_32x32x16_bf16 v[82:97], v[160:163], v[126:129], v[82:97]
	s_nop 15
	s_nop 7
	s_nop 9
	s_cmp_eq_u32 s51, s96
	s_cbranch_scc1 .Lcb1_d
	v_mul_f32_e64 v252, -v251, v178
	v_add_f32_e32 v156, v252, v98
	v_add_f32_e32 v157, v252, v99
	v_add_f32_e32 v99, v252, v83
	v_add_f32_e32 v98, v252, v82
	v_add_f32_e32 v161, v252, v101
	v_add_f32_e32 v160, v252, v100
	v_add_f32_e32 v153, v252, v85
	v_add_f32_e32 v152, v252, v84
	v_add_f32_e32 v165, v252, v103
	v_add_f32_e32 v164, v252, v102
	v_add_f32_e32 v103, v252, v87
	v_add_f32_e32 v102, v252, v86
	v_add_f32_e32 v167, v252, v105
	v_add_f32_e32 v166, v252, v104
	v_add_f32_e32 v155, v252, v89
	v_add_f32_e32 v154, v252, v88
	v_add_f32_e32 v159, v252, v107
	v_add_f32_e32 v158, v252, v106
	v_add_f32_e32 v101, v252, v91
	v_add_f32_e32 v100, v252, v90
	v_add_f32_e32 v163, v252, v109
	v_add_f32_e32 v162, v252, v108
	v_add_f32_e32 v105, v252, v93
	v_add_f32_e32 v104, v252, v92
	v_add_f32_e32 v111, v252, v111
	v_add_f32_e32 v110, v252, v110
	v_add_f32_e32 v107, v252, v95
	v_add_f32_e32 v106, v252, v94
	v_add_f32_e32 v113, v252, v113
	v_add_f32_e32 v112, v252, v112
	v_add_f32_e32 v109, v252, v97
	v_add_f32_e32 v108, v252, v96
	s_branch .Lcb1_j
.Lcb1_d:
	v_add_f32_e32 v179, -1.0, v178
	v_fma_f32 v156, -v142, |v178|, v98
	v_fma_f32 v157, -v143, |v179|, v99
	v_pk_add_f32 v[98:99], v[178:179], s[8:9] op_sel_hi:[1,0]
	s_nop 0
	v_fma_f32 v99, -v143, |v99|, v83
	v_fma_f32 v98, -v142, |v98|, v82
	v_pk_add_f32 v[82:83], v[178:179], s[10:11] op_sel_hi:[0,1]
	v_fma_f32 v161, -v143, |v83|, v101
	v_fma_f32 v160, -v142, |v82|, v100
	v_pk_add_f32 v[82:83], v[82:83], s[8:9] op_sel_hi:[1,0]
	v_fma_f32 v153, -v143, |v83|, v85
	v_fma_f32 v152, -v142, |v82|, v84
	v_pk_add_f32 v[82:83], v[178:179], s[22:23] op_sel_hi:[0,1]
	v_fma_f32 v165, -v143, |v83|, v103
	v_fma_f32 v164, -v142, |v82|, v102
	v_pk_add_f32 v[82:83], v[82:83], s[8:9] op_sel_hi:[1,0]
	v_fma_f32 v103, -v143, |v83|, v87
	v_fma_f32 v102, -v142, |v82|, v86
	v_pk_add_f32 v[82:83], v[178:179], s[34:35] op_sel_hi:[0,1]
	v_fma_f32 v167, -v143, |v83|, v105
	v_fma_f32 v166, -v142, |v82|, v104
	v_pk_add_f32 v[82:83], v[82:83], s[8:9] op_sel_hi:[1,0]
	v_fma_f32 v155, -v143, |v83|, v89
	v_fma_f32 v154, -v142, |v82|, v88
	v_pk_add_f32 v[82:83], v[178:179], s[36:37] op_sel_hi:[0,1]
	v_fma_f32 v159, -v143, |v83|, v107
	v_fma_f32 v158, -v142, |v82|, v106
	v_pk_add_f32 v[82:83], v[82:83], s[8:9] op_sel_hi:[1,0]
	v_fma_f32 v101, -v143, |v83|, v91
	v_fma_f32 v100, -v142, |v82|, v90
	v_pk_add_f32 v[82:83], v[178:179], s[38:39] op_sel_hi:[0,1]
	v_fma_f32 v163, -v143, |v83|, v109
	v_fma_f32 v162, -v142, |v82|, v108
	v_pk_add_f32 v[82:83], v[82:83], s[8:9] op_sel_hi:[1,0]
	v_fma_f32 v105, -v143, |v83|, v93
	v_fma_f32 v104, -v142, |v82|, v92
	v_pk_add_f32 v[82:83], v[178:179], s[40:41] op_sel_hi:[0,1]
	v_fma_f32 v111, -v143, |v83|, v111
	v_fma_f32 v110, -v142, |v82|, v110
	v_pk_add_f32 v[82:83], v[82:83], s[8:9] op_sel_hi:[1,0]
	v_fma_f32 v107, -v143, |v83|, v95
	v_fma_f32 v106, -v142, |v82|, v94
	v_pk_add_f32 v[82:83], v[178:179], s[42:43] op_sel_hi:[0,1]
	v_fma_f32 v113, -v143, |v83|, v113
	v_fma_f32 v112, -v142, |v82|, v112
	v_pk_add_f32 v[82:83], v[82:83], s[8:9] op_sel_hi:[1,0]
	v_fma_f32 v109, -v143, |v83|, v97
	v_fma_f32 v108, -v142, |v82|, v96

; #define LAS __attribute__((address_space(3)))
; template <int DQK, int DV, bool BIAS> ...
;     ...
;         const LAS unsigned char* kb = lds + buf * KBUF + r32 * KP + hi * 16;
; #pragma unroll
;         for (int ks = 0; ks < NKS; ++ks) {
;             const bf16x8 k0 = *(const LAS bf16x8*)(kb + ks * 32), k1 = *(const LAS bf16x8*)(kb + 32 * KP + ks * 32);
;             if (ks == 0) { p0 = __builtin_amdgcn_mfma_f32_32x32x16_bf16(k0, qf[0], negm, 0, 0, 0); p1 = __builtin_amdgcn_mfma_f32_32x32x16_bf16(k1, qf[0], negm, 0, 0, 0); }
;             else { p0 = __builtin_amdgcn_mfma_f32_32x32x16_bf16(k0, qf[ks], p0, 0, 0, 0); p1 = __builtin_amdgcn_mfma_f32_32x32x16_bf16(k1, qf[ks], p1, 0, 0, 0); }
;         }
;         if (BIAS) {
;             asm volatile("s_nop 15\n\ts_nop 7" : "+v"(p0), "+v"(p1));
;             const float d0 = qp - (float)(t * 64 + 4 * hi);
; #pragma unroll
;             for (int r = 0; r < 16; ++r) { const float dk = d0 - (float)((r & 3) + 8 * (r >> 2)); p0[r] = p0[r] - sl2 * fabsf(dk); p1[r] = p1[r] - sl2 * fabsf(dk - 32.f); }
.Lcb2_ok:
	ds_read_b128 v[192:195], v175 offset:9216
	ds_read_b128 v[196:199], v175 offset:9248
	v_add_f32_e32 v156, v157, v156
	v_add_f32_e32 v156, v160, v156
	s_waitcnt lgkmcnt(1)
	v_mfma_f32_32x32x16_bf16 v[98:113], v[192:195], v[114:117], v[66:81]
	ds_read_b128 v[192:195], v175 offset:13824
	ds_read_b128 v[200:203], v175 offset:13856
	v_add_f32_e32 v156, v161, v156
	v_add_f32_e32 v156, v164, v156
	v_add_f32_e32 v150, v150, v156
	v_add_f32_e32 v150, v165, v150
	v_add_f32_e32 v150, v166, v150
	v_add_f32_e32 v150, v167, v150
	s_waitcnt lgkmcnt(1)
	v_mfma_f32_32x32x16_bf16 v[82:97], v[192:195], v[114:117], v[234:249]
	v_add_f32_e32 v150, v177, v150
	v_add_f32_e32 v150, v178, v150
	v_add_f32_e32 v150, v158, v150
	v_add_f32_e32 v150, v159, v150
	ds_read_b128 v[164:167], v175 offset:9280
	v_add_f32_e32 v150, v162, v150
	v_add_f32_e32 v150, v163, v150
	v_mfma_f32_32x32x16_bf16 v[98:113], v[196:199], v[118:121], v[98:113]
	v_add_f32_e32 v150, v179, v150
	v_add_f32_e32 v150, v180, v150
	v_add_f32_e32 v150, v181, v150
	v_add_f32_e32 v150, v152, v150
	ds_read_b128 v[156:159], v175 offset:13888
	ds_read_b128 v[160:163], v175 offset:9312
	v_add_f32_e32 v150, v153, v150
	v_add_f32_e32 v150, v182, v150
	s_waitcnt lgkmcnt(3)
	v_mfma_f32_32x32x16_bf16 v[82:97], v[200:203], v[118:121], v[82:97]
	v_add_f32_e32 v150, v183, v150
	v_add_f32_e32 v150, v154, v150
	v_add_f32_e32 v150, v155, v150
	v_add_f32_e32 v150, v184, v150
	v_add_f32_e32 v150, v185, v150
	v_add_u32_e32 v152, 64, v173
	v_add_f32_e32 v150, v186, v150
	s_waitcnt lgkmcnt(2)
	v_mfma_f32_32x32x16_bf16 v[98:113], v[164:167], v[122:125], v[98:113]
	ds_read_b128 v[164:167], v175 offset:13920
	v_cvt_f32_u32_e32 v152, v152
	v_add_f32_e32 v150, v187, v150
	v_add_f32_e32 v150, v188, v150
	v_add_f32_e32 v150, v191, v150
	v_add_f32_e32 v150, v189, v150
	v_add_f32_e32 v150, v190, v150
	s_waitcnt lgkmcnt(2)
	v_mfma_f32_32x32x16_bf16 v[82:97], v[156:159], v[122:125], v[82:97]
	v_add_f32_e32 v158, v151, v150
	s_waitcnt lgkmcnt(1)
	v_mfma_f32_32x32x16_bf16 v[98:113], v[160:163], v[126:129], v[98:113]
	v_sub_f32_e32 v160, v172, v152
	s_waitcnt lgkmcnt(0)
	v_mfma_f32_32x32x16_bf16 v[82:97], v[164:167], v[126:129], v[82:97]
	s_nop 15
	s_nop 7
	s_nop 5
	s_add_i32 s100, s51, 1
	s_cmp_eq_u32 s100, s96
	s_cbranch_scc1 .Lcb2_d
	v_mul_f32_e64 v252, -v251, v160
	v_add_f32_e32 v150, v252, v98
	v_add_f32_e32 v151, v252, v99
	v_add_f32_e32 v83, v252, v83
	v_add_f32_e32 v82, v252, v82
	v_add_f32_e32 v153, v252, v101
	v_add_f32_e32 v152, v252, v100
	v_add_f32_e32 v99, v252, v85
	v_add_f32_e32 v98, v252, v84
	v_add_f32_e32 v155, v252, v103
	v_add_f32_e32 v154, v252, v102
	v_add_f32_e32 v101, v252, v87
	v_add_f32_e32 v100, v252, v86
	v_add_f32_e32 v157, v252, v105
	v_add_f32_e32 v156, v252, v104
	v_add_f32_e32 v103, v252, v89
	v_add_f32_e32 v102, v252, v88
	v_add_f32_e32 v105, v252, v107
	v_add_f32_e32 v104, v252, v106
	v_add_f32_e32 v107, v252, v109
	v_add_f32_e32 v106, v252, v108
	v_add_f32_e32 v85, v252, v91
	v_add_f32_e32 v84, v252, v90
	v_add_f32_e32 v87, v252, v93
	v_add_f32_e32 v86, v252, v92
	v_add_f32_e32 v93, v252, v111
	v_add_f32_e32 v92, v252, v110
	v_add_f32_e32 v89, v252, v95
	v_add_f32_e32 v88, v252, v94
	v_add_f32_e32 v95, v252, v113
	v_add_f32_e32 v94, v252, v112
	v_add_f32_e32 v91, v252, v97
	v_add_f32_e32 v90, v252, v96
	s_branch .Lcb2_j
.Lcb2_d:
	v_add_f32_e32 v161, -1.0, v160
	v_fma_f32 v150, -v142, |v160|, v98
	v_fma_f32 v151, -v143, |v161|, v99
	v_pk_add_f32 v[98:99], v[160:161], s[8:9] op_sel_hi:[1,0]
	s_nop 0
	v_fma_f32 v83, -v143, |v99|, v83
	v_fma_f32 v82, -v142, |v98|, v82
	s_nop 0
	v_pk_add_f32 v[98:99], v[160:161], s[10:11] op_sel_hi:[0,1]
	v_fma_f32 v153, -v143, |v99|, v101
	v_fma_f32 v152, -v142, |v98|, v100
	v_pk_add_f32 v[98:99], v[98:99], s[8:9] op_sel_hi:[1,0]
	v_fma_f32 v99, -v143, |v99|, v85
	v_fma_f32 v98, -v142, |v98|, v84
	v_pk_add_f32 v[84:85], v[160:161], s[22:23] op_sel_hi:[0,1]
	v_fma_f32 v155, -v143, |v85|, v103
	v_fma_f32 v154, -v142, |v84|, v102
	v_pk_add_f32 v[84:85], v[84:85], s[8:9] op_sel_hi:[1,0]
	v_fma_f32 v101, -v143, |v85|, v87
	v_fma_f32 v100, -v142, |v84|, v86
	v_pk_add_f32 v[84:85], v[160:161], s[34:35] op_sel_hi:[0,1]
	v_fma_f32 v157, -v143, |v85|, v105
	v_fma_f32 v156, -v142, |v84|, v104
	v_pk_add_f32 v[84:85], v[84:85], s[8:9] op_sel_hi:[1,0]
	v_fma_f32 v103, -v143, |v85|, v89
	v_fma_f32 v102, -v142, |v84|, v88
	v_pk_add_f32 v[84:85], v[160:161], s[36:37] op_sel_hi:[0,1]
	v_fma_f32 v105, -v143, |v85|, v107
	v_fma_f32 v104, -v142, |v84|, v106
	v_pk_add_f32 v[86:87], v[160:161], s[38:39] op_sel_hi:[0,1]
	v_pk_add_f32 v[84:85], v[84:85], s[8:9] op_sel_hi:[1,0]
	v_fma_f32 v107, -v143, |v87|, v109
	v_fma_f32 v106, -v142, |v86|, v108
	v_fma_f32 v85, -v143, |v85|, v91
	v_fma_f32 v84, -v142, |v84|, v90
	v_pk_add_f32 v[86:87], v[86:87], s[8:9] op_sel_hi:[1,0]
	v_pk_add_f32 v[88:89], v[160:161], s[40:41] op_sel_hi:[0,1]
	v_fma_f32 v87, -v143, |v87|, v93
	v_fma_f32 v86, -v142, |v86|, v92
	v_fma_f32 v93, -v143, |v89|, v111
	v_fma_f32 v92, -v142, |v88|, v110
	v_pk_add_f32 v[88:89], v[88:89], s[8:9] op_sel_hi:[1,0]
	v_fma_f32 v89, -v143, |v89|, v95
	v_fma_f32 v88, -v142, |v88|, v94
	v_pk_add_f32 v[90:91], v[160:161], s[42:43] op_sel_hi:[0,1]
	v_fma_f32 v95, -v143, |v91|, v113
	v_fma_f32 v94, -v142, |v90|, v112
	v_pk_add_f32 v[90:91], v[90:91], s[8:9] op_sel_hi:[1,0]
	v_fma_f32 v91, -v143, |v91|, v97
	v_fma_f32 v90, -v142, |v90|, v96

; #define LAS __attribute__((address_space(3)))
; template <int DQK, int DV, bool BIAS> ...
;     ...
;         const LAS unsigned char* kb = lds + buf * KBUF + r32 * KP + hi * 16;
; #pragma unroll
;         for (int ks = 0; ks < NKS; ++ks) {
;             const bf16x8 k0 = *(const LAS bf16x8*)(kb + ks * 32), k1 = *(const LAS bf16x8*)(kb + 32 * KP + ks * 32);
;             if (ks == 0) { p0 = __builtin_amdgcn_mfma_f32_32x32x16_bf16(k0, qf[0], negm, 0, 0, 0); p1 = __builtin_amdgcn_mfma_f32_32x32x16_bf16(k1, qf[0], negm, 0, 0, 0); }
;             else { p0 = __builtin_amdgcn_mfma_f32_32x32x16_bf16(k0, qf[ks], p0, 0, 0, 0); p1 = __builtin_amdgcn_mfma_f32_32x32x16_bf16(k1, qf[ks], p1, 0, 0, 0); }
;         }
;         if (BIAS) {
;             asm volatile("s_nop 15\n\ts_nop 7" : "+v"(p0), "+v"(p1));
;             const float d0 = qp - (float)(t * 64 + 4 * hi);
; #pragma unroll
;             for (int r = 0; r < 16; ++r) { const float dk = d0 - (float)((r & 3) + 8 * (r >> 2)); p0[r] = p0[r] - sl2 * fabsf(dk); p1[r] = p1[r] - sl2 * fabsf(dk - 32.f); }
.Lcb3_ok:
	ds_read_b128 v[82:85], v179
	ds_read_b128 v[152:155], v179 offset:32
	ds_read_b128 v[156:159], v179 offset:4608
	ds_read_b128 v[160:163], v179 offset:4640
	v_cvt_f32_u32_e32 v150, v177
	s_waitcnt lgkmcnt(3)
	v_mfma_f32_32x32x16_bf16 v[98:113], v[82:85], v[114:117], v[66:81]
	v_sub_f32_e32 v182, v176, v150
	s_waitcnt lgkmcnt(1)
	v_mfma_f32_32x32x16_bf16 v[82:97], v[156:159], v[114:117], v[234:249]
	v_mfma_f32_32x32x16_bf16 v[98:113], v[152:155], v[118:121], v[98:113]
	ds_read_b128 v[152:155], v179 offset:64
	ds_read_b128 v[156:159], v179 offset:96
	s_waitcnt lgkmcnt(2)
	v_mfma_f32_32x32x16_bf16 v[82:97], v[160:163], v[118:121], v[82:97]
	s_waitcnt lgkmcnt(1)
	v_mfma_f32_32x32x16_bf16 v[98:113], v[152:155], v[122:125], v[98:113]
	ds_read_b128 v[152:155], v179 offset:4672
	ds_read_b128 v[160:163], v179 offset:4704
	s_waitcnt lgkmcnt(1)
	v_mfma_f32_32x32x16_bf16 v[82:97], v[152:155], v[122:125], v[82:97]
	v_mfma_f32_32x32x16_bf16 v[98:113], v[156:159], v[126:129], v[98:113]
	s_waitcnt lgkmcnt(0)
	v_mfma_f32_32x32x16_bf16 v[82:97], v[160:163], v[126:129], v[82:97]
	s_nop 15
	s_nop 7
	s_nop 9
	s_cmp_eq_u32 s7, s96
	s_cbranch_scc1 .Lcb3_d
	v_mul_f32_e64 v252, -v251, v182
	v_add_f32_e32 v156, v252, v98
	v_add_f32_e32 v157, v252, v99
	v_add_f32_e32 v99, v252, v83
	v_add_f32_e32 v98, v252, v82
	v_add_f32_e32 v161, v252, v101
	v_add_f32_e32 v160, v252, v100
	v_add_f32_e32 v153, v252, v85
	v_add_f32_e32 v152, v252, v84
	v_add_f32_e32 v165, v252, v103
	v_add_f32_e32 v164, v252, v102
	v_add_f32_e32 v103, v252, v87
	v_add_f32_e32 v102, v252, v86
	v_add_f32_e32 v167, v252, v105
	v_add_f32_e32 v166, v252, v104
	v_add_f32_e32 v155, v252, v89
	v_add_f32_e32 v154, v252, v88
	v_add_f32_e32 v159, v252, v107
	v_add_f32_e32 v158, v252, v106
	v_add_f32_e32 v101, v252, v91
	v_add_f32_e32 v100, v252, v90
	v_add_f32_e32 v163, v252, v109
	v_add_f32_e32 v162, v252, v108
	v_add_f32_e32 v105, v252, v93
	v_add_f32_e32 v104, v252, v92
	v_add_f32_e32 v111, v252, v111
	v_add_f32_e32 v110, v252, v110
	v_add_f32_e32 v107, v252, v95
	v_add_f32_e32 v106, v252, v94
	v_add_f32_e32 v113, v252, v113
	v_add_f32_e32 v112, v252, v112
	v_add_f32_e32 v109, v252, v97
	v_add_f32_e32 v108, v252, v96
	s_branch .Lcb3_j
.Lcb3_d:
	v_add_f32_e32 v183, -1.0, v182
	v_fma_f32 v156, -v142, |v182|, v98
	v_fma_f32 v157, -v143, |v183|, v99
	v_pk_add_f32 v[98:99], v[182:183], s[6:7] op_sel_hi:[1,0]
	s_nop 0
	v_fma_f32 v99, -v143, |v99|, v83
	v_fma_f32 v98, -v142, |v98|, v82
	v_pk_add_f32 v[82:83], v[182:183], s[8:9] op_sel_hi:[0,1]
	v_fma_f32 v161, -v143, |v83|, v101
	v_fma_f32 v160, -v142, |v82|, v100
	v_pk_add_f32 v[82:83], v[82:83], s[6:7] op_sel_hi:[1,0]
	v_fma_f32 v153, -v143, |v83|, v85
	v_fma_f32 v152, -v142, |v82|, v84
	v_pk_add_f32 v[82:83], v[182:183], s[10:11] op_sel_hi:[0,1]
	v_fma_f32 v165, -v143, |v83|, v103
	v_fma_f32 v164, -v142, |v82|, v102
	v_pk_add_f32 v[82:83], v[82:83], s[6:7] op_sel_hi:[1,0]
	v_fma_f32 v103, -v143, |v83|, v87
	v_fma_f32 v102, -v142, |v82|, v86
	v_pk_add_f32 v[82:83], v[182:183], s[22:23] op_sel_hi:[0,1]
	v_fma_f32 v167, -v143, |v83|, v105
	v_fma_f32 v166, -v142, |v82|, v104
	v_pk_add_f32 v[82:83], v[82:83], s[6:7] op_sel_hi:[1,0]
	v_fma_f32 v155, -v143, |v83|, v89
	v_fma_f32 v154, -v142, |v82|, v88
	v_pk_add_f32 v[82:83], v[182:183], s[34:35] op_sel_hi:[0,1]
	v_fma_f32 v159, -v143, |v83|, v107
	v_fma_f32 v158, -v142, |v82|, v106
	v_pk_add_f32 v[82:83], v[82:83], s[6:7] op_sel_hi:[1,0]
	v_fma_f32 v101, -v143, |v83|, v91
	v_fma_f32 v100, -v142, |v82|, v90
	v_pk_add_f32 v[82:83], v[182:183], s[36:37] op_sel_hi:[0,1]
	v_fma_f32 v163, -v143, |v83|, v109
	v_fma_f32 v162, -v142, |v82|, v108
	v_pk_add_f32 v[82:83], v[82:83], s[6:7] op_sel_hi:[1,0]
	v_fma_f32 v105, -v143, |v83|, v93
	v_fma_f32 v104, -v142, |v82|, v92
	v_pk_add_f32 v[82:83], v[182:183], s[38:39] op_sel_hi:[0,1]
	v_fma_f32 v111, -v143, |v83|, v111
	v_fma_f32 v110, -v142, |v82|, v110
	v_pk_add_f32 v[82:83], v[82:83], s[6:7] op_sel_hi:[1,0]
	v_fma_f32 v107, -v143, |v83|, v95
	v_fma_f32 v106, -v142, |v82|, v94
	v_pk_add_f32 v[82:83], v[182:183], s[40:41] op_sel_hi:[0,1]
	v_fma_f32 v113, -v143, |v83|, v113
	v_fma_f32 v112, -v142, |v82|, v112
	v_pk_add_f32 v[82:83], v[82:83], s[6:7] op_sel_hi:[1,0]
	v_fma_f32 v109, -v143, |v83|, v97
	v_fma_f32 v108, -v142, |v82|, v96

; #define LAS __attribute__((address_space(3)))
; template <int DQK, int DV, bool BIAS> ...
;     ...
;         const LAS unsigned char* kb = lds + buf * KBUF + r32 * KP + hi * 16;
; #pragma unroll
;         for (int ks = 0; ks < NKS; ++ks) {
;             const bf16x8 k0 = *(const LAS bf16x8*)(kb + ks * 32), k1 = *(const LAS bf16x8*)(kb + 32 * KP + ks * 32);
;             if (ks == 0) { p0 = __builtin_amdgcn_mfma_f32_32x32x16_bf16(k0, qf[0], negm, 0, 0, 0); p1 = __builtin_amdgcn_mfma_f32_32x32x16_bf16(k1, qf[0], negm, 0, 0, 0); }
;             else { p0 = __builtin_amdgcn_mfma_f32_32x32x16_bf16(k0, qf[ks], p0, 0, 0, 0); p1 = __builtin_amdgcn_mfma_f32_32x32x16_bf16(k1, qf[ks], p1, 0, 0, 0); }
;         }
;         if (BIAS) {
;             asm volatile("s_nop 15\n\ts_nop 7" : "+v"(p0), "+v"(p1));
;             const float d0 = qp - (float)(t * 64 + 4 * hi);
; #pragma unroll
;             for (int r = 0; r < 16; ++r) { const float dk = d0 - (float)((r & 3) + 8 * (r >> 2)); p0[r] = p0[r] - sl2 * fabsf(dk); p1[r] = p1[r] - sl2 * fabsf(dk - 32.f); }
.Lcb4_ok:
	ds_read_b128 v[196:199], v179 offset:9216
	ds_read_b128 v[200:203], v179 offset:9248
	v_add_f32_e32 v156, v157, v156
	v_add_f32_e32 v156, v160, v156
	s_waitcnt lgkmcnt(1)
	v_mfma_f32_32x32x16_bf16 v[98:113], v[196:199], v[114:117], v[66:81]
	ds_read_b128 v[196:199], v179 offset:13824
	ds_read_b128 v[204:207], v179 offset:13856
	v_add_f32_e32 v156, v161, v156
	v_add_f32_e32 v156, v164, v156
	v_add_f32_e32 v150, v150, v156
	v_add_f32_e32 v150, v165, v150
	v_add_f32_e32 v150, v166, v150
	v_add_f32_e32 v150, v167, v150
	s_waitcnt lgkmcnt(1)
	v_mfma_f32_32x32x16_bf16 v[82:97], v[196:199], v[114:117], v[234:249]
	v_add_f32_e32 v150, v181, v150
	v_add_f32_e32 v150, v182, v150
	v_add_f32_e32 v150, v158, v150
	v_add_f32_e32 v150, v159, v150
	ds_read_b128 v[164:167], v179 offset:9280
	v_add_f32_e32 v150, v162, v150
	v_add_f32_e32 v150, v163, v150
	v_mfma_f32_32x32x16_bf16 v[98:113], v[200:203], v[118:121], v[98:113]
	v_add_f32_e32 v150, v183, v150
	v_add_f32_e32 v150, v184, v150
	v_add_f32_e32 v150, v185, v150
	v_add_f32_e32 v150, v152, v150
	ds_read_b128 v[156:159], v179 offset:13888
	ds_read_b128 v[160:163], v179 offset:9312
	v_add_f32_e32 v150, v153, v150
	v_add_f32_e32 v150, v186, v150
	s_waitcnt lgkmcnt(3)
	v_mfma_f32_32x32x16_bf16 v[82:97], v[204:207], v[118:121], v[82:97]
	v_add_f32_e32 v150, v187, v150
	v_add_f32_e32 v150, v154, v150
	v_add_f32_e32 v150, v155, v150
	v_add_f32_e32 v150, v188, v150
	v_add_f32_e32 v150, v189, v150
	v_add_u32_e32 v152, 64, v177
	v_add_f32_e32 v150, v190, v150
	s_waitcnt lgkmcnt(2)
	v_mfma_f32_32x32x16_bf16 v[98:113], v[164:167], v[122:125], v[98:113]
	ds_read_b128 v[164:167], v179 offset:13920
	v_cvt_f32_u32_e32 v152, v152
	v_add_f32_e32 v150, v191, v150
	v_add_f32_e32 v150, v192, v150
	v_add_f32_e32 v150, v195, v150
	v_add_f32_e32 v150, v193, v150
	v_add_f32_e32 v150, v194, v150
	s_waitcnt lgkmcnt(2)
	v_mfma_f32_32x32x16_bf16 v[82:97], v[156:159], v[122:125], v[82:97]
	v_add_f32_e32 v158, v151, v150
	s_waitcnt lgkmcnt(1)
	v_mfma_f32_32x32x16_bf16 v[98:113], v[160:163], v[126:129], v[98:113]
	v_sub_f32_e32 v160, v176, v152
	s_waitcnt lgkmcnt(0)
	v_mfma_f32_32x32x16_bf16 v[82:97], v[164:167], v[126:129], v[82:97]
	s_nop 15
	s_nop 7
	s_nop 5
	s_add_i32 s100, s7, 1
	s_cmp_eq_u32 s100, s96
	s_cbranch_scc1 .Lcb4_d
	v_mul_f32_e64 v252, -v251, v160
	v_add_f32_e32 v150, v252, v98
	v_add_f32_e32 v151, v252, v99
	v_add_f32_e32 v83, v252, v83
	v_add_f32_e32 v82, v252, v82
	v_add_f32_e32 v153, v252, v101
	v_add_f32_e32 v152, v252, v100
	v_add_f32_e32 v99, v252, v85
	v_add_f32_e32 v98, v252, v84
	v_add_f32_e32 v155, v252, v103
	v_add_f32_e32 v154, v252, v102
	v_add_f32_e32 v101, v252, v87
	v_add_f32_e32 v100, v252, v86
	v_add_f32_e32 v157, v252, v105
	v_add_f32_e32 v156, v252, v104
	v_add_f32_e32 v103, v252, v89
	v_add_f32_e32 v102, v252, v88
	v_add_f32_e32 v105, v252, v107
	v_add_f32_e32 v104, v252, v106
	v_add_f32_e32 v107, v252, v109
	v_add_f32_e32 v106, v252, v108
	v_add_f32_e32 v85, v252, v91
	v_add_f32_e32 v84, v252, v90
	v_add_f32_e32 v87, v252, v93
	v_add_f32_e32 v86, v252, v92
	v_add_f32_e32 v93, v252, v111
	v_add_f32_e32 v92, v252, v110
	v_add_f32_e32 v89, v252, v95
	v_add_f32_e32 v88, v252, v94
	v_add_f32_e32 v95, v252, v113
	v_add_f32_e32 v94, v252, v112
	v_add_f32_e32 v91, v252, v97
	v_add_f32_e32 v90, v252, v96
	s_branch .Lcb4_j
.Lcb4_d:
	v_add_f32_e32 v161, -1.0, v160
	v_fma_f32 v150, -v142, |v160|, v98
	v_fma_f32 v151, -v143, |v161|, v99
	v_pk_add_f32 v[98:99], v[160:161], s[6:7] op_sel_hi:[1,0]
	s_nop 0
	v_fma_f32 v83, -v143, |v99|, v83
	v_fma_f32 v82, -v142, |v98|, v82
	s_nop 0
	v_pk_add_f32 v[98:99], v[160:161], s[8:9] op_sel_hi:[0,1]
	v_fma_f32 v153, -v143, |v99|, v101
	v_fma_f32 v152, -v142, |v98|, v100
	v_pk_add_f32 v[98:99], v[98:99], s[6:7] op_sel_hi:[1,0]
	v_fma_f32 v99, -v143, |v99|, v85
	v_fma_f32 v98, -v142, |v98|, v84
	v_pk_add_f32 v[84:85], v[160:161], s[10:11] op_sel_hi:[0,1]
	v_fma_f32 v155, -v143, |v85|, v103
	v_fma_f32 v154, -v142, |v84|, v102
	v_pk_add_f32 v[84:85], v[84:85], s[6:7] op_sel_hi:[1,0]
	v_fma_f32 v101, -v143, |v85|, v87
	v_fma_f32 v100, -v142, |v84|, v86
	v_pk_add_f32 v[84:85], v[160:161], s[22:23] op_sel_hi:[0,1]
	v_fma_f32 v157, -v143, |v85|, v105
	v_fma_f32 v156, -v142, |v84|, v104
	v_pk_add_f32 v[84:85], v[84:85], s[6:7] op_sel_hi:[1,0]
	v_fma_f32 v103, -v143, |v85|, v89
	v_fma_f32 v102, -v142, |v84|, v88
	v_pk_add_f32 v[84:85], v[160:161], s[34:35] op_sel_hi:[0,1]
	v_fma_f32 v105, -v143, |v85|, v107
	v_fma_f32 v104, -v142, |v84|, v106
	v_pk_add_f32 v[86:87], v[160:161], s[36:37] op_sel_hi:[0,1]
	v_pk_add_f32 v[84:85], v[84:85], s[6:7] op_sel_hi:[1,0]
	v_fma_f32 v107, -v143, |v87|, v109
	v_fma_f32 v106, -v142, |v86|, v108
	v_fma_f32 v85, -v143, |v85|, v91
	v_fma_f32 v84, -v142, |v84|, v90
	v_pk_add_f32 v[86:87], v[86:87], s[6:7] op_sel_hi:[1,0]
	v_pk_add_f32 v[88:89], v[160:161], s[38:39] op_sel_hi:[0,1]
	v_fma_f32 v87, -v143, |v87|, v93
	v_fma_f32 v86, -v142, |v86|, v92
	v_fma_f32 v93, -v143, |v89|, v111
	v_fma_f32 v92, -v142, |v88|, v110
	v_pk_add_f32 v[88:89], v[88:89], s[6:7] op_sel_hi:[1,0]
	v_fma_f32 v89, -v143, |v89|, v95
	v_fma_f32 v88, -v142, |v88|, v94
	v_pk_add_f32 v[90:91], v[160:161], s[40:41] op_sel_hi:[0,1]
	v_fma_f32 v95, -v143, |v91|, v113
	v_fma_f32 v94, -v142, |v90|, v112
	v_pk_add_f32 v[90:91], v[90:91], s[6:7] op_sel_hi:[1,0]
	v_fma_f32 v91, -v143, |v91|, v97
	v_fma_f32 v90, -v142, |v90|, v96

; #define LAS __attribute__((address_space(3)))
; __device__ __forceinline__ unsigned cvtpk(float lo, float hi) { typedef __bf16 bf2 __attribute__((ext_vector_type(2))); f32x2 v = {lo, hi}; bf2 b = __builtin_convertvector(v, bf2); return __builtin_bit_cast(unsigned, b); }
; template <int DIR, bool PASS2>
; __device__ __forceinline__ void s5_sub(LAS unsigned char* ulds, const bf16x8 (&bb)[8], const bf16x8 (&bc)[4], float lbr, float lbi, float& sr, float& si, f32x4& yacc, int sub, int lane) {
;     ...
;     u32x4 uw = {0u, 0u, 0u, 0u};
;     if (kq < 2) uw = *(const LAS u32x4*)(ulds + (sub * 16 + hq) * 32 + kq * 16);
;     const bf16x8 ua = __builtin_bit_cast(bf16x8, uw);
;     LAS float* xp = xlds + (4 * kq) * S5_XP + hq;
;     f32x4 xs[8];
; #pragma unroll
;     for (int nt = 0; nt < 8; ++nt) xs[nt] = __builtin_amdgcn_mfma_f32_16x16x32_bf16(ua, bb[nt], (f32x4){0.f, 0.f, 0.f, 0.f}, 0, 0, 0);
;     asm volatile("s_nop 15\n\ts_nop 15" : "+v"(xs[0]), "+v"(xs[1]), "+v"(xs[2]), "+v"(xs[3]), "+v"(xs[4]), "+v"(xs[5]), "+v"(xs[6]), "+v"(xs[7]));
; #pragma unroll
;     for (int nt = 0; nt < 8; ++nt) { xp[16 * nt] = xs[nt][0]; xp[16 * nt + S5_XP] = xs[nt][1]; xp[16 * nt + 2 * S5_XP] = xs[nt][2]; xp[16 * nt + 3 * S5_XP] = xs[nt][3]; }
;     asm volatile("s_waitcnt lgkmcnt(0)" ::: "memory");
;     const LAS float* xr = xlds + 2 * lane; LAS unsigned char* sw = slds + lane * 4;
; #pragma unroll
;     for (int q = 0; q < 16; ++q) {
;         const int jj = DIR ? 15 - q : q;
;         const f32x2 x = *(const LAS f32x2*)(xr + jj * S5_XP);
;         const float nr = lbr * sr - lbi * si + x[0], ni = lbr * si + lbi * sr + x[1]; sr = nr; si = ni;
;         if (PASS2) *(LAS unsigned*)(sw + jj * 272) = cvtpk(sr, si);
;     }
.LBB0_1703:
	s_or_b64 exec, exec, s[10:11]
	s_waitcnt lgkmcnt(0)
	v_mfma_f32_16x16x32_bf16 v[76:79], v[34:37], v[2:5], 0
	v_add_u32_e32 v61, 0x1000, v39
	v_add_u32_e32 v75, 0x1400, v39
	v_mfma_f32_16x16x32_bf16 v[80:83], v[34:37], v[6:9], 0
	v_mfma_f32_16x16x32_bf16 v[84:87], v[34:37], v[10:13], 0
	v_mfma_f32_16x16x32_bf16 v[88:91], v[34:37], v[14:17], 0
	v_mfma_f32_16x16x32_bf16 v[92:95], v[34:37], v[18:21], 0
	v_mfma_f32_16x16x32_bf16 v[96:99], v[34:37], v[22:25], 0
	v_mfma_f32_16x16x32_bf16 v[100:103], v[34:37], v[26:29], 0
	v_mfma_f32_16x16x32_bf16 v[34:37], v[34:37], v[30:33], 0
	s_nop 3
	s_nop 1
	ds_write2_b32 v61, v76, v80 offset1:16
	ds_write2_b32 v61, v77, v81 offset0:132 offset1:148
	ds_write2_b32 v75, v78, v82 offset0:8 offset1:24
	ds_write2_b32 v75, v79, v83 offset0:140 offset1:156
	ds_write2_b32 v61, v84, v88 offset0:32 offset1:48
	ds_write2_b32 v61, v85, v89 offset0:164 offset1:180
	ds_write2_b32 v75, v86, v90 offset0:40 offset1:56
	ds_write2_b32 v75, v87, v91 offset0:172 offset1:188
	ds_write2_b32 v61, v92, v96 offset0:64 offset1:80
	ds_write2_b32 v61, v93, v97 offset0:196 offset1:212
	ds_write2_b32 v75, v94, v98 offset0:72 offset1:88
	ds_write2_b32 v75, v95, v99 offset0:204 offset1:220
	ds_write2_b32 v61, v100, v34 offset0:96 offset1:112
	ds_write2_b32 v61, v101, v35 offset0:228 offset1:244
	ds_write2_b32 v75, v102, v36 offset0:104 offset1:120
	ds_write2_b32 v75, v103, v37 offset0:236 offset1:252
	v_add_u32_e32 v75, s27, v40
	s_waitcnt lgkmcnt(0)
	v_add_u32_e32 v80, 0x2800, v75
	ds_read2_b64 v[34:37], v80 offset0:156 offset1:222
	v_pk_mul_f32 v[76:77], v[56:57], v[66:67] op_sel_hi:[1,0]
	s_nop 0
	v_pk_fma_f32 v[78:79], v[58:59], v[60:61], v[76:77] neg_lo:[0,0,1] neg_hi:[0,0,1]
	v_pk_fma_f32 v[60:61], v[58:59], v[60:61], v[76:77] op_sel_hi:[1,0,1]
	s_nop 0
	v_mov_b32_e32 v79, v61
	s_waitcnt lgkmcnt(0)
	v_pk_add_f32 v[36:37], v[78:79], v[36:37]
	ds_read2_b64 v[76:79], v80 offset0:24 offset1:90
	v_mul_f32_e32 v60, v59, v37
	v_pk_fma_f32 v[60:61], v[58:59], v[36:37], v[60:61] op_sel_hi:[1,1,0] neg_lo:[0,0,1] neg_hi:[0,0,1]
	v_pk_mul_f32 v[36:37], v[56:57], v[36:37]
	v_pk_add_f32 v[60:61], v[34:35], v[60:61]
	v_add_f32_e32 v36, v37, v36
	v_pk_add_f32 v[34:35], v[34:35], v[36:37] op_sel:[1,0] op_sel_hi:[1,0]
	v_add_u32_e32 v80, 0x2000, v75
	v_pk_mul_f32 v[34:35], v[56:57], v[34:35]
	s_nop 0
	v_pk_fma_f32 v[36:37], v[58:59], v[60:61], v[34:35] neg_lo:[0,0,1] neg_hi:[0,0,1]
	v_pk_fma_f32 v[34:35], v[58:59], v[60:61], v[34:35] op_sel_hi:[1,0,1]
	s_nop 0
	v_mov_b32_e32 v37, v35
	s_waitcnt lgkmcnt(0)
	v_pk_add_f32 v[34:35], v[78:79], v[36:37]
	s_nop 0
	v_mul_f32_e32 v36, v59, v35
	v_pk_fma_f32 v[36:37], v[58:59], v[34:35], v[36:37] op_sel_hi:[1,1,0] neg_lo:[0,0,1] neg_hi:[0,0,1]
	v_pk_mul_f32 v[78:79], v[56:57], v[34:35]
	v_pk_add_f32 v[60:61], v[76:77], v[36:37]
	ds_read2_b64 v[34:37], v80 offset0:148 offset1:214
	v_add_f32_e32 v66, v79, v78
	v_pk_add_f32 v[76:77], v[76:77], v[66:67] op_sel:[1,0] op_sel_hi:[1,0]
	s_nop 0
	v_pk_mul_f32 v[76:77], v[56:57], v[76:77]
	s_nop 0
	v_pk_fma_f32 v[78:79], v[58:59], v[60:61], v[76:77] neg_lo:[0,0,1] neg_hi:[0,0,1]
	v_pk_fma_f32 v[60:61], v[58:59], v[60:61], v[76:77] op_sel_hi:[1,0,1]
	s_nop 0
	v_mov_b32_e32 v79, v61
	s_waitcnt lgkmcnt(0)
; #define LAS __attribute__((address_space(3)))
; __device__ __forceinline__ unsigned cvtpk(float lo, float hi) { typedef __bf16 bf2 __attribute__((ext_vector_type(2))); f32x2 v = {lo, hi}; bf2 b = __builtin_convertvector(v, bf2); return __builtin_bit_cast(unsigned, b); }
; template <int DIR, bool PASS2>
; __device__ __forceinline__ void s5_sub(LAS unsigned char* ulds, const bf16x8 (&bb)[8], const bf16x8 (&bc)[4], float lbr, float lbi, float& sr, float& si, f32x4& yacc, int sub, int lane) {
;     ...
;     const LAS float* xr = xlds + 2 * lane; LAS unsigned char* sw = slds + lane * 4;
; #pragma unroll
;     for (int q = 0; q < 16; ++q) {
;         const int jj = DIR ? 15 - q : q;
;         const f32x2 x = *(const LAS f32x2*)(xr + jj * S5_XP);
;         const float nr = lbr * sr - lbi * si + x[0], ni = lbr * si + lbi * sr + x[1]; sr = nr; si = ni;
;         if (PASS2) *(LAS unsigned*)(sw + jj * 272) = cvtpk(sr, si);
;     }
; template <int DIR, bool PASS2>
; __device__ __forceinline__ void s5_dir(LAS unsigned char* ulds, const bf16x8 (&bb)[8], const bf16x8 (&bc)[4], float lbr, float lbi, float& sr, float& si, f32x4 (&yacc)[8], int lane) {
;     ...
;         for (int sb = 0; sb < 8; ++sb) { const int sub = DIR ? 7 - sb : sb; s5_sub<DIR, false>(ulds, bb, bc, lbr, lbi, sr, si, yacc[0], sub, lane); }
	v_pk_add_f32 v[36:37], v[36:37], v[78:79]
	ds_read2_b64 v[76:79], v80 offset0:16 offset1:82
	v_mul_f32_e32 v60, v59, v37
	v_pk_fma_f32 v[60:61], v[58:59], v[36:37], v[60:61] op_sel_hi:[1,1,0] neg_lo:[0,0,1] neg_hi:[0,0,1]
	v_pk_mul_f32 v[36:37], v[56:57], v[36:37]
	v_pk_add_f32 v[60:61], v[34:35], v[60:61]
	v_add_f32_e32 v36, v37, v36
	v_pk_add_f32 v[34:35], v[34:35], v[36:37] op_sel:[1,0] op_sel_hi:[1,0]
	v_add_u32_e32 v80, 0x1800, v75
	v_pk_mul_f32 v[34:35], v[56:57], v[34:35]
	v_add_u32_e32 v75, 0x1000, v75
	v_pk_fma_f32 v[36:37], v[58:59], v[60:61], v[34:35] neg_lo:[0,0,1] neg_hi:[0,0,1]
	v_pk_fma_f32 v[34:35], v[58:59], v[60:61], v[34:35] op_sel_hi:[1,0,1]
	s_nop 0
	v_mov_b32_e32 v37, v35
	s_waitcnt lgkmcnt(0)
	v_pk_add_f32 v[34:35], v[78:79], v[36:37]
	s_nop 0
	v_pk_mul_f32 v[78:79], v[56:57], v[34:35]
	v_pk_mul_f32 v[60:61], v[58:59], v[34:35]
	ds_read2_b64 v[34:37], v80 offset0:140 offset1:206
	v_add_f32_e32 v66, v79, v78
	v_pk_add_f32 v[78:79], v[76:77], v[66:67] op_sel:[1,0] op_sel_hi:[1,0]
	v_sub_f32_e32 v60, v60, v61
	v_pk_mul_f32 v[78:79], v[56:57], v[78:79]
	v_add_f32_e32 v60, v76, v60
	v_pk_fma_f32 v[76:77], v[58:59], v[60:61], v[78:79] op_sel_hi:[1,0,1]
	v_pk_fma_f32 v[60:61], v[58:59], v[60:61], v[78:79] op_sel_hi:[1,0,1] neg_lo:[0,0,1] neg_hi:[0,0,1]
	s_nop 0
	v_mov_b32_e32 v61, v77
	s_waitcnt lgkmcnt(0)
	v_pk_add_f32 v[36:37], v[36:37], v[60:61]
	ds_read2_b64 v[76:79], v80 offset0:8 offset1:74
	v_pk_mul_f32 v[60:61], v[58:59], v[36:37]
	v_pk_mul_f32 v[36:37], v[56:57], v[36:37]
	s_nop 0
	v_add_f32_e32 v36, v37, v36
	v_pk_add_f32 v[36:37], v[34:35], v[36:37] op_sel:[1,0] op_sel_hi:[1,0]
	v_sub_f32_e32 v35, v60, v61
	v_pk_mul_f32 v[36:37], v[56:57], v[36:37]
	v_add_f32_e32 v34, v34, v35
	v_pk_fma_f32 v[60:61], v[58:59], v[34:35], v[36:37] op_sel_hi:[1,0,1]
	v_pk_fma_f32 v[34:35], v[58:59], v[34:35], v[36:37] op_sel_hi:[1,0,1] neg_lo:[0,0,1] neg_hi:[0,0,1]
	s_nop 0
	v_mov_b32_e32 v35, v61
	s_waitcnt lgkmcnt(0)
	v_pk_add_f32 v[34:35], v[78:79], v[34:35]
	s_nop 0
	v_mul_f32_e32 v36, v59, v35
	v_pk_fma_f32 v[36:37], v[58:59], v[34:35], v[36:37] op_sel_hi:[1,1,0] neg_lo:[0,0,1] neg_hi:[0,0,1]
	v_pk_mul_f32 v[78:79], v[56:57], v[34:35]
	v_pk_add_f32 v[60:61], v[76:77], v[36:37]
	ds_read2_b64 v[34:37], v75 offset0:132 offset1:198
	v_add_f32_e32 v66, v79, v78
	v_pk_add_f32 v[76:77], v[76:77], v[66:67] op_sel:[1,0] op_sel_hi:[1,0]
	s_nop 0
	v_pk_mul_f32 v[76:77], v[56:57], v[76:77]
	s_nop 0
	v_pk_fma_f32 v[80:81], v[58:59], v[60:61], v[76:77] neg_lo:[0,0,1] neg_hi:[0,0,1]
	v_pk_fma_f32 v[60:61], v[58:59], v[60:61], v[76:77] op_sel_hi:[1,0,1]
	ds_read2_b64 v[76:79], v75 offset1:66
	v_mov_b32_e32 v81, v61
	s_waitcnt lgkmcnt(1)
	v_pk_add_f32 v[36:37], v[36:37], v[80:81]
	s_waitcnt lgkmcnt(0)
	s_nop 0
	v_pk_mul_f32 v[60:61], v[64:65], v[36:37]
	s_nop 0
	v_pk_fma_f32 v[80:81], v[62:63], v[36:37], v[60:61] op_sel:[0,0,1] op_sel_hi:[1,1,0] neg_lo:[0,0,1] neg_hi:[0,0,1]
	v_pk_fma_f32 v[36:37], v[62:63], v[36:37], v[60:61] op_sel:[0,0,1] op_sel_hi:[1,1,0]
	s_nop 0
	v_mov_b32_e32 v81, v37
	v_pk_add_f32 v[34:35], v[34:35], v[80:81]
	s_nop 0
	v_pk_mul_f32 v[36:37], v[64:65], v[34:35]
	s_nop 0
	v_pk_fma_f32 v[60:61], v[62:63], v[34:35], v[36:37] op_sel:[0,0,1] op_sel_hi:[1,1,0] neg_lo:[0,0,1] neg_hi:[0,0,1]
	v_pk_fma_f32 v[34:35], v[62:63], v[34:35], v[36:37] op_sel:[0,0,1] op_sel_hi:[1,1,0]
	s_nop 0
	v_mov_b32_e32 v61, v35
	s_waitcnt lgkmcnt(0)
	v_pk_add_f32 v[34:35], v[78:79], v[60:61]
	s_nop 0
	v_pk_mul_f32 v[36:37], v[64:65], v[34:35]
	s_nop 0
	v_pk_fma_f32 v[60:61], v[62:63], v[34:35], v[36:37] op_sel:[0,0,1] op_sel_hi:[1,1,0] neg_lo:[0,0,1] neg_hi:[0,0,1]
	v_pk_fma_f32 v[34:35], v[62:63], v[34:35], v[36:37] op_sel:[0,0,1] op_sel_hi:[1,1,0]
	s_nop 0
	v_mov_b32_e32 v61, v35
	v_pk_add_f32 v[60:61], v[76:77], v[60:61]
	s_addk_i32 s44, 0xfe00
	s_cmpk_lg_i32 s44, 0xfe00
	v_mov_b32_e32 v66, v61
	s_cbranch_scc0 .LBB0_1706

; #define LAS __attribute__((address_space(3)))
; __device__ __forceinline__ unsigned cvtpk(float lo, float hi) { typedef __bf16 bf2 __attribute__((ext_vector_type(2))); f32x2 v = {lo, hi}; bf2 b = __builtin_convertvector(v, bf2); return __builtin_bit_cast(unsigned, b); }
; template <int DIR, bool PASS2>
; __device__ __forceinline__ void s5_sub(LAS unsigned char* ulds, const bf16x8 (&bb)[8], const bf16x8 (&bc)[4], float lbr, float lbi, float& sr, float& si, f32x4& yacc, int sub, int lane) {
;     ...
;     u32x4 uw = {0u, 0u, 0u, 0u};
;     if (kq < 2) uw = *(const LAS u32x4*)(ulds + (sub * 16 + hq) * 32 + kq * 16);
;     const bf16x8 ua = __builtin_bit_cast(bf16x8, uw);
;     LAS float* xp = xlds + (4 * kq) * S5_XP + hq;
;     f32x4 xs[8];
; #pragma unroll
;     for (int nt = 0; nt < 8; ++nt) xs[nt] = __builtin_amdgcn_mfma_f32_16x16x32_bf16(ua, bb[nt], (f32x4){0.f, 0.f, 0.f, 0.f}, 0, 0, 0);
;     asm volatile("s_nop 15\n\ts_nop 15" : "+v"(xs[0]), "+v"(xs[1]), "+v"(xs[2]), "+v"(xs[3]), "+v"(xs[4]), "+v"(xs[5]), "+v"(xs[6]), "+v"(xs[7]));
; #pragma unroll
;     for (int nt = 0; nt < 8; ++nt) { xp[16 * nt] = xs[nt][0]; xp[16 * nt + S5_XP] = xs[nt][1]; xp[16 * nt + 2 * S5_XP] = xs[nt][2]; xp[16 * nt + 3 * S5_XP] = xs[nt][3]; }
;     asm volatile("s_waitcnt lgkmcnt(0)" ::: "memory");
;     const LAS float* xr = xlds + 2 * lane; LAS unsigned char* sw = slds + lane * 4;
; #pragma unroll
;     for (int q = 0; q < 16; ++q) {
;         const int jj = DIR ? 15 - q : q;
;         const f32x2 x = *(const LAS f32x2*)(xr + jj * S5_XP);
;         const float nr = lbr * sr - lbi * si + x[0], ni = lbr * si + lbi * sr + x[1]; sr = nr; si = ni;
;         if (PASS2) *(LAS unsigned*)(sw + jj * 272) = cvtpk(sr, si);
;     }
.LBB0_1709:
	s_or_b64 exec, exec, s[10:11]
	s_waitcnt lgkmcnt(0)
	v_mfma_f32_16x16x32_bf16 v[76:79], v[34:37], v[2:5], 0
	v_add_u32_e32 v66, 0x1000, v39
	v_add_u32_e32 v75, 0x1400, v39
	v_mfma_f32_16x16x32_bf16 v[80:83], v[34:37], v[6:9], 0
	v_mfma_f32_16x16x32_bf16 v[84:87], v[34:37], v[10:13], 0
	v_mfma_f32_16x16x32_bf16 v[88:91], v[34:37], v[14:17], 0
	v_mfma_f32_16x16x32_bf16 v[92:95], v[34:37], v[18:21], 0
	v_mfma_f32_16x16x32_bf16 v[96:99], v[34:37], v[22:25], 0
	v_mfma_f32_16x16x32_bf16 v[100:103], v[34:37], v[26:29], 0
	v_mfma_f32_16x16x32_bf16 v[34:37], v[34:37], v[30:33], 0
	s_nop 3
	s_nop 1
	ds_write2_b32 v66, v76, v80 offset1:16
	ds_write2_b32 v66, v77, v81 offset0:132 offset1:148
	ds_write2_b32 v75, v78, v82 offset0:8 offset1:24
	ds_write2_b32 v75, v79, v83 offset0:140 offset1:156
	ds_write2_b32 v66, v84, v88 offset0:32 offset1:48
	ds_write2_b32 v66, v85, v89 offset0:164 offset1:180
	ds_write2_b32 v75, v86, v90 offset0:40 offset1:56
	ds_write2_b32 v75, v87, v91 offset0:172 offset1:188
	ds_write2_b32 v66, v92, v96 offset0:64 offset1:80
	ds_write2_b32 v66, v93, v97 offset0:196 offset1:212
	ds_write2_b32 v75, v94, v98 offset0:72 offset1:88
	ds_write2_b32 v75, v95, v99 offset0:204 offset1:220
	ds_write2_b32 v66, v100, v34 offset0:96 offset1:112
	ds_write2_b32 v66, v101, v35 offset0:228 offset1:244
	ds_write2_b32 v75, v102, v36 offset0:104 offset1:120
	ds_write2_b32 v75, v103, v37 offset0:236 offset1:252
	v_add_u32_e32 v75, s27, v40
	s_waitcnt lgkmcnt(0)
	v_add_u32_e32 v78, 0x1000, v75
	ds_read2_b64 v[34:37], v78 offset1:66
	v_mul_f32_e32 v66, v59, v61
	v_pk_fma_f32 v[76:77], v[58:59], v[60:61], v[66:67] op_sel_hi:[1,1,0] neg_lo:[0,0,1] neg_hi:[0,0,1]
	v_pk_mul_f32 v[60:61], v[56:57], v[60:61]
	v_add_u32_e32 v66, 0x1800, v75
	v_add_f32_e32 v60, v60, v61
	s_waitcnt lgkmcnt(0)
	v_pk_add_f32 v[76:77], v[76:77], v[34:35]
	v_pk_add_f32 v[34:35], v[60:61], v[34:35] op_sel:[0,1] op_sel_hi:[0,1]
	v_pk_mul_f32 v[34:35], v[56:57], v[34:35]
	ds_read2_b64 v[80:83], v66 offset0:8 offset1:74
	v_pk_fma_f32 v[60:61], v[58:59], v[76:77], v[34:35] neg_lo:[0,0,1] neg_hi:[0,0,1]
	v_pk_fma_f32 v[34:35], v[58:59], v[76:77], v[34:35] op_sel_hi:[1,0,1]
	ds_read2_b64 v[76:79], v78 offset0:132 offset1:198
	v_mov_b32_e32 v61, v35
	v_pk_add_f32 v[34:35], v[36:37], v[60:61]
	s_nop 0
	v_pk_mul_f32 v[36:37], v[64:65], v[34:35]
	s_nop 0
	v_pk_fma_f32 v[60:61], v[62:63], v[34:35], v[36:37] op_sel:[0,0,1] op_sel_hi:[1,1,0]
	v_pk_fma_f32 v[34:35], v[62:63], v[34:35], v[36:37] op_sel:[0,0,1] op_sel_hi:[1,1,0] neg_lo:[0,0,1] neg_hi:[0,0,1]
	s_nop 0
	v_mov_b32_e32 v35, v61
	s_waitcnt lgkmcnt(0)
	v_pk_add_f32 v[34:35], v[76:77], v[34:35]
	s_nop 0
	v_pk_mul_f32 v[36:37], v[64:65], v[34:35]
	s_nop 0
	v_pk_fma_f32 v[60:61], v[62:63], v[34:35], v[36:37] op_sel:[0,0,1] op_sel_hi:[1,1,0]
	v_pk_fma_f32 v[34:35], v[62:63], v[34:35], v[36:37] op_sel:[0,0,1] op_sel_hi:[1,1,0] neg_lo:[0,0,1] neg_hi:[0,0,1]
	s_nop 0
	v_mov_b32_e32 v35, v61
	v_pk_add_f32 v[34:35], v[78:79], v[34:35]
	s_nop 0
	v_pk_mul_f32 v[36:37], v[64:65], v[34:35]
	s_nop 0
	v_pk_fma_f32 v[60:61], v[62:63], v[34:35], v[36:37] op_sel:[0,0,1] op_sel_hi:[1,1,0]
	v_pk_fma_f32 v[34:35], v[62:63], v[34:35], v[36:37] op_sel:[0,0,1] op_sel_hi:[1,1,0] neg_lo:[0,0,1] neg_hi:[0,0,1]
	s_nop 0
	v_mov_b32_e32 v35, v61
	v_pk_add_f32 v[34:35], v[80:81], v[34:35]
	s_nop 0
	v_mul_f32_e32 v36, v59, v35
	v_pk_fma_f32 v[60:61], v[58:59], v[34:35], v[36:37] op_sel_hi:[1,1,0] neg_lo:[0,0,1] neg_hi:[0,0,1]
	v_mul_f32_e32 v36, v56, v34
	v_pk_fma_f32 v[80:81], v[56:57], v[34:35], v[36:37] op_sel_hi:[1,1,0]
	ds_read2_b64 v[34:37], v66 offset0:140 offset1:206
	v_mov_b32_e32 v61, v81
	v_pk_add_f32 v[60:61], v[82:83], v[60:61]
	v_add_u32_e32 v66, 0x2000, v75
	v_pk_mul_f32 v[80:81], v[64:65], v[60:61]
	ds_read2_b64 v[76:79], v66 offset0:16 offset1:82
	v_pk_fma_f32 v[82:83], v[62:63], v[60:61], v[80:81] op_sel:[0,0,1] op_sel_hi:[1,1,0] neg_lo:[0,0,1] neg_hi:[0,0,1]
	v_pk_fma_f32 v[60:61], v[62:63], v[60:61], v[80:81] op_sel:[0,0,1] op_sel_hi:[1,1,0]
	s_nop 0
	v_mov_b32_e32 v83, v61
	s_waitcnt lgkmcnt(1)
; #define LAS __attribute__((address_space(3)))
; __device__ __forceinline__ unsigned cvtpk(float lo, float hi) { typedef __bf16 bf2 __attribute__((ext_vector_type(2))); f32x2 v = {lo, hi}; bf2 b = __builtin_convertvector(v, bf2); return __builtin_bit_cast(unsigned, b); }
; template <int DIR, bool PASS2>
; __device__ __forceinline__ void s5_sub(LAS unsigned char* ulds, const bf16x8 (&bb)[8], const bf16x8 (&bc)[4], float lbr, float lbi, float& sr, float& si, f32x4& yacc, int sub, int lane) {
;     ...
;     const LAS float* xr = xlds + 2 * lane; LAS unsigned char* sw = slds + lane * 4;
; #pragma unroll
;     for (int q = 0; q < 16; ++q) {
;         const int jj = DIR ? 15 - q : q;
;         const f32x2 x = *(const LAS f32x2*)(xr + jj * S5_XP);
;         const float nr = lbr * sr - lbi * si + x[0], ni = lbr * si + lbi * sr + x[1]; sr = nr; si = ni;
;         if (PASS2) *(LAS unsigned*)(sw + jj * 272) = cvtpk(sr, si);
;     }
; template <int DIR, bool PASS2>
; __device__ __forceinline__ void s5_dir(LAS unsigned char* ulds, const bf16x8 (&bb)[8], const bf16x8 (&bc)[4], float lbr, float lbi, float& sr, float& si, f32x4 (&yacc)[8], int lane) {
;     ...
; #pragma unroll 1
;         for (int sb = 0; sb < 8; ++sb) { const int sub = DIR ? 7 - sb : sb; s5_sub<DIR, false>(ulds, bb, bc, lbr, lbi, sr, si, yacc[0], sub, lane); }
	v_pk_add_f32 v[34:35], v[34:35], v[82:83]
	s_nop 0
	v_pk_mul_f32 v[60:61], v[64:65], v[34:35]
	s_nop 0
	v_pk_fma_f32 v[80:81], v[62:63], v[34:35], v[60:61] op_sel:[0,0,1] op_sel_hi:[1,1,0] neg_lo:[0,0,1] neg_hi:[0,0,1]
	v_pk_fma_f32 v[34:35], v[62:63], v[34:35], v[60:61] op_sel:[0,0,1] op_sel_hi:[1,1,0]
	s_nop 0
	v_mov_b32_e32 v81, v35
	v_pk_add_f32 v[34:35], v[36:37], v[80:81]
	s_nop 0
	v_pk_mul_f32 v[36:37], v[64:65], v[34:35]
	s_nop 0
	v_pk_fma_f32 v[60:61], v[62:63], v[34:35], v[36:37] op_sel:[0,0,1] op_sel_hi:[1,1,0] neg_lo:[0,0,1] neg_hi:[0,0,1]
	v_pk_fma_f32 v[34:35], v[62:63], v[34:35], v[36:37] op_sel:[0,0,1] op_sel_hi:[1,1,0]
	s_nop 0
	v_mov_b32_e32 v61, v35
	s_waitcnt lgkmcnt(0)
	v_pk_add_f32 v[60:61], v[76:77], v[60:61]
	ds_read2_b64 v[34:37], v66 offset0:148 offset1:214
	v_pk_mul_f32 v[76:77], v[64:65], v[60:61]
	v_add_u32_e32 v66, 0x2800, v75
	v_pk_fma_f32 v[84:85], v[62:63], v[60:61], v[76:77] op_sel:[0,0,1] op_sel_hi:[1,1,0] neg_lo:[0,0,1] neg_hi:[0,0,1]
	v_pk_fma_f32 v[60:61], v[62:63], v[60:61], v[76:77] op_sel:[0,0,1] op_sel_hi:[1,1,0]
	ds_read2_b64 v[80:83], v66 offset0:24 offset1:90
	v_mov_b32_e32 v85, v61
	v_pk_add_f32 v[60:61], v[78:79], v[84:85]
	s_nop 0
	v_pk_mul_f32 v[76:77], v[64:65], v[60:61]
	s_nop 0
	v_pk_fma_f32 v[78:79], v[62:63], v[60:61], v[76:77] op_sel:[0,0,1] op_sel_hi:[1,1,0] neg_lo:[0,0,1] neg_hi:[0,0,1]
	v_pk_fma_f32 v[60:61], v[62:63], v[60:61], v[76:77] op_sel:[0,0,1] op_sel_hi:[1,1,0]
	s_nop 0
	v_mov_b32_e32 v79, v61
	s_waitcnt lgkmcnt(1)
	v_pk_add_f32 v[34:35], v[34:35], v[78:79]
	s_nop 0
	v_pk_mul_f32 v[60:61], v[64:65], v[34:35]
	s_nop 0
	v_pk_fma_f32 v[76:77], v[62:63], v[34:35], v[60:61] op_sel:[0,0,1] op_sel_hi:[1,1,0] neg_lo:[0,0,1] neg_hi:[0,0,1]
	v_pk_fma_f32 v[34:35], v[62:63], v[34:35], v[60:61] op_sel:[0,0,1] op_sel_hi:[1,1,0]
	s_nop 0
	v_mov_b32_e32 v77, v35
	v_pk_add_f32 v[34:35], v[36:37], v[76:77]
	s_nop 0
	v_pk_mul_f32 v[36:37], v[64:65], v[34:35]
	s_nop 0
	v_pk_fma_f32 v[60:61], v[62:63], v[34:35], v[36:37] op_sel:[0,0,1] op_sel_hi:[1,1,0] neg_lo:[0,0,1] neg_hi:[0,0,1]
	v_pk_fma_f32 v[34:35], v[62:63], v[34:35], v[36:37] op_sel:[0,0,1] op_sel_hi:[1,1,0]
	s_nop 0
	v_mov_b32_e32 v61, v35
	s_waitcnt lgkmcnt(0)
	v_pk_add_f32 v[60:61], v[80:81], v[60:61]
	ds_read2_b64 v[34:37], v66 offset0:156 offset1:222
	v_pk_mul_f32 v[76:77], v[64:65], v[60:61]
	s_waitcnt lgkmcnt(0)
	s_nop 0
	v_pk_fma_f32 v[78:79], v[62:63], v[60:61], v[76:77] op_sel:[0,0,1] op_sel_hi:[1,1,0] neg_lo:[0,0,1] neg_hi:[0,0,1]
	v_pk_fma_f32 v[60:61], v[62:63], v[60:61], v[76:77] op_sel:[0,0,1] op_sel_hi:[1,1,0]
	s_nop 0
	v_mov_b32_e32 v79, v61
	v_pk_add_f32 v[60:61], v[82:83], v[78:79]
	s_nop 0
	v_pk_mul_f32 v[76:77], v[64:65], v[60:61]
	s_nop 0
	v_pk_fma_f32 v[78:79], v[62:63], v[60:61], v[76:77] op_sel:[0,0,1] op_sel_hi:[1,1,0] neg_lo:[0,0,1] neg_hi:[0,0,1]
	v_pk_fma_f32 v[60:61], v[62:63], v[60:61], v[76:77] op_sel:[0,0,1] op_sel_hi:[1,1,0]
	s_nop 0
	v_mov_b32_e32 v79, v61
	s_waitcnt lgkmcnt(0)
	v_pk_add_f32 v[34:35], v[34:35], v[78:79]
	s_nop 0
	v_pk_mul_f32 v[60:61], v[64:65], v[34:35]
	s_nop 0
	v_pk_fma_f32 v[76:77], v[62:63], v[34:35], v[60:61] op_sel:[0,0,1] op_sel_hi:[1,1,0] neg_lo:[0,0,1] neg_hi:[0,0,1]
	v_pk_fma_f32 v[34:35], v[62:63], v[34:35], v[60:61] op_sel:[0,0,1] op_sel_hi:[1,1,0]
	s_nop 0
	v_mov_b32_e32 v77, v35
	v_pk_add_f32 v[60:61], v[36:37], v[76:77]
	s_addk_i32 s44, 0x200
	s_cmpk_eq_i32 s44, 0x1000
	s_cbranch_scc1 .LBB0_1698

; #define LAS __attribute__((address_space(3)))
; __device__ __forceinline__ unsigned cvtpk(float lo, float hi) { typedef __bf16 bf2 __attribute__((ext_vector_type(2))); f32x2 v = {lo, hi}; bf2 b = __builtin_convertvector(v, bf2); return __builtin_bit_cast(unsigned, b); }
; template <int DIR, bool PASS2>
; __device__ __forceinline__ void s5_sub(LAS unsigned char* ulds, const bf16x8 (&bb)[8], const bf16x8 (&bc)[4], float lbr, float lbi, float& sr, float& si, f32x4& yacc, int sub, int lane) {
;     ...
;     u32x4 uw = {0u, 0u, 0u, 0u};
;     if (kq < 2) uw = *(const LAS u32x4*)(ulds + (sub * 16 + hq) * 32 + kq * 16);
;     const bf16x8 ua = __builtin_bit_cast(bf16x8, uw);
;     LAS float* xp = xlds + (4 * kq) * S5_XP + hq;
;     f32x4 xs[8];
; #pragma unroll
;     for (int nt = 0; nt < 8; ++nt) xs[nt] = __builtin_amdgcn_mfma_f32_16x16x32_bf16(ua, bb[nt], (f32x4){0.f, 0.f, 0.f, 0.f}, 0, 0, 0);
;     asm volatile("s_nop 15\n\ts_nop 15" : "+v"(xs[0]), "+v"(xs[1]), "+v"(xs[2]), "+v"(xs[3]), "+v"(xs[4]), "+v"(xs[5]), "+v"(xs[6]), "+v"(xs[7]));
; #pragma unroll
;     for (int nt = 0; nt < 8; ++nt) { xp[16 * nt] = xs[nt][0]; xp[16 * nt + S5_XP] = xs[nt][1]; xp[16 * nt + 2 * S5_XP] = xs[nt][2]; xp[16 * nt + 3 * S5_XP] = xs[nt][3]; }
;     asm volatile("s_waitcnt lgkmcnt(0)" ::: "memory");
;     const LAS float* xr = xlds + 2 * lane; LAS unsigned char* sw = slds + lane * 4;
; #pragma unroll
;     for (int q = 0; q < 16; ++q) {
;         const int jj = DIR ? 15 - q : q;
;         const f32x2 x = *(const LAS f32x2*)(xr + jj * S5_XP);
;         const float nr = lbr * sr - lbi * si + x[0], ni = lbr * si + lbi * sr + x[1]; sr = nr; si = ni;
;         if (PASS2) *(LAS unsigned*)(sw + jj * 272) = cvtpk(sr, si);
; __device__ __forceinline__ void s5h_pass2(PPtr P, int li, LAS unsigned char* lds, int gw, int NGW, int wave, int lane) {
;     ...
;                 bf16_t* drow = dst + (size_t)(sub * 16 + 4 * kq) * LDP;
;                 float yf[4] = {0.f, 0.f, 0.f, 0.f};
;                 if (dir) {
; #pragma unroll
;                     for (int i = 0; i < 4; ++i) yf[i] = bf1(drow[(size_t)i * LDP]);
;                 }
;                 f32x4 acc = {0.f, 0.f, 0.f, 0.f};
;                 if (dir == 0) s5_sub<0, true>(ulds, bb, bc, lbr, lbi, sr, si, acc, sub, lane); else s5_sub<1, true>(ulds, bb, bc, lbr, lbi, sr, si, acc, sub, lane);
.LBB0_1921:
	s_and_b64 s[10:11], s[52:53], exec
	s_cselect_b32 s10, s38, s70
	v_lshl_or_b32 v64, s10, 4, v76
	v_mul_lo_u32 v68, v64, s74
	v_cndmask_b32_e64 v50, 0, 1, s[66:67]
	v_lshl_add_u64 v[56:57], v[68:69], 1, v[94:95]
	v_cmp_ne_u32_e64 s[10:11], 1, v50
	s_andn2_b64 vcc, exec, s[66:67]
	s_mov_b64 s[68:69], -1
	s_cbranch_vccnz .LBB0_1927
	v_add_co_u32_e32 v50, vcc, 0x1000, v56
	s_nop 1
	v_addc_co_u32_e32 v51, vcc, 0, v57, vcc
	v_add_co_u32_e32 v52, vcc, 0x3000, v56
	s_nop 1
	v_addc_co_u32_e32 v53, vcc, 0, v57, vcc
	v_add_co_u32_e32 v62, vcc, 0x4000, v56
	s_nop 1
	v_addc_co_u32_e32 v63, vcc, 0, v57, vcc
	global_load_ushort v60, v[56:57], off
	global_load_ushort v58, v[50:51], off offset:2368
	global_load_ushort v59, v[52:53], off offset:640
	global_load_ushort v65, v[62:63], off offset:3008
	v_mov_b32_e32 v50, 0
	v_mov_b32_e32 v51, 0
	v_mov_b32_e32 v52, 0
	v_mov_b32_e32 v53, 0
	s_and_saveexec_b64 s[68:69], s[8:9]
	ds_read_b128 v[50:53], v91
	s_or_b64 exec, exec, s[68:69]
	s_waitcnt lgkmcnt(0)
	v_mfma_f32_16x16x32_bf16 v[106:109], v[50:53], v[2:5], 0
	v_add_u32_e32 v61, v67, v75
	v_add_u32_e32 v62, 0x1000, v61
	v_add_u32_e32 v61, 0x1400, v61
	v_mfma_f32_16x16x32_bf16 v[126:129], v[50:53], v[6:9], 0
	v_mul_f32_e32 v68, v101, v102
	v_add_u32_e32 v110, s27, v77
	v_mfma_f32_16x16x32_bf16 v[130:133], v[50:53], v[10:13], 0
	v_mfma_f32_16x16x32_bf16 v[134:137], v[50:53], v[14:17], 0
	v_mfma_f32_16x16x32_bf16 v[138:141], v[50:53], v[18:21], 0
	v_mfma_f32_16x16x32_bf16 v[142:145], v[50:53], v[22:25], 0
	v_mfma_f32_16x16x32_bf16 v[146:149], v[50:53], v[26:29], 0
	v_mfma_f32_16x16x32_bf16 v[50:53], v[50:53], v[30:33], 0
	s_nop 3
	ds_write2_b32 v62, v106, v126 offset1:16
	ds_write2_b32 v62, v107, v127 offset0:132 offset1:148
	ds_write2_b32 v61, v108, v128 offset0:8 offset1:24
	ds_write2_b32 v61, v109, v129 offset0:140 offset1:156
	ds_write2_b32 v62, v130, v134 offset0:32 offset1:48
	ds_write2_b32 v62, v131, v135 offset0:164 offset1:180
	ds_write2_b32 v61, v132, v136 offset0:40 offset1:56
	ds_write2_b32 v61, v133, v137 offset0:172 offset1:188
	ds_write2_b32 v62, v138, v142 offset0:64 offset1:80
	ds_write2_b32 v62, v139, v143 offset0:196 offset1:212
	ds_write2_b32 v61, v140, v144 offset0:72 offset1:88
	ds_write2_b32 v61, v141, v145 offset0:204 offset1:220
	ds_write2_b32 v62, v146, v50 offset0:96 offset1:112
	ds_write2_b32 v62, v147, v51 offset0:228 offset1:244
	ds_write2_b32 v61, v148, v52 offset0:104 offset1:120
	ds_write2_b32 v61, v149, v53 offset0:236 offset1:252
	v_add_u32_e32 v61, s27, v70
	s_waitcnt lgkmcnt(0)
	v_add_u32_e32 v105, 0x2800, v61
	ds_read2_b64 v[50:53], v105 offset0:156 offset1:222
	v_mul_f32_e32 v62, v101, v103
	v_pk_fma_f32 v[62:63], v[100:101], v[102:103], v[62:63] op_sel_hi:[1,1,0] neg_lo:[0,0,1] neg_hi:[0,0,1]
	v_pk_fma_f32 v[106:107], v[100:101], v[102:103], v[68:69] op_sel:[0,1,0] op_sel_hi:[1,0,0]
	v_add_u32_e32 v111, 0x2000, v61
	s_waitcnt lgkmcnt(0)
	v_pk_add_f32 v[62:63], v[62:63], v[52:53]
	v_pk_add_f32 v[52:53], v[106:107], v[52:53] op_sel:[0,1] op_sel_hi:[1,0]
	s_nop 0
	v_mov_b32_e32 v63, v52
	v_mul_f32_e32 v68, v101, v52
	v_cvt_pk_bf16_f32 v108, v62, v52
	v_pk_fma_f32 v[106:107], v[100:101], v[62:63], v[68:69] op_sel_hi:[1,1,0] neg_lo:[0,0,1] neg_hi:[0,0,1]
	v_mov_b32_e32 v53, v62
	v_mul_f32_e32 v62, v101, v62
	v_pk_fma_f32 v[52:53], v[100:101], v[52:53], v[62:63] op_sel_hi:[1,1,0]
	v_pk_add_f32 v[106:107], v[50:51], v[106:107]
	v_pk_add_f32 v[62:63], v[50:51], v[52:53] op_sel:[1,0] op_sel_hi:[0,1]
	ds_read2_b64 v[50:53], v105 offset0:24 offset1:90
	v_cvt_pk_bf16_f32 v63, v106, v62
	v_add_u32_e32 v68, 0x3e00, v110
	v_mov_b32_e32 v107, v62
	ds_write2_b32 v68, v63, v108 offset0:120 offset1:188
	v_mul_f32_e32 v68, v101, v62
	v_pk_fma_f32 v[108:109], v[100:101], v[106:107], v[68:69] op_sel_hi:[1,1,0] neg_lo:[0,0,1] neg_hi:[0,0,1]
	v_mov_b32_e32 v63, v106
	v_mul_f32_e32 v68, v101, v106
	v_pk_fma_f32 v[62:63], v[100:101], v[62:63], v[68:69] op_sel_hi:[1,1,0]
	s_waitcnt lgkmcnt(1)
	v_pk_add_f32 v[108:109], v[52:53], v[108:109]
	v_pk_add_f32 v[52:53], v[52:53], v[62:63] op_sel:[1,0] op_sel_hi:[0,1]
	v_mov_b32_e32 v109, v52
	v_mul_f32_e32 v62, v101, v52
	v_mov_b32_e32 v53, v108
	v_mul_f32_e32 v68, v101, v108
	v_cvt_pk_bf16_f32 v105, v108, v52
	v_pk_fma_f32 v[62:63], v[100:101], v[108:109], v[62:63] op_sel_hi:[1,1,0] neg_lo:[0,0,1] neg_hi:[0,0,1]
	v_pk_fma_f32 v[52:53], v[100:101], v[52:53], v[68:69] op_sel_hi:[1,1,0]
	v_pk_add_f32 v[62:63], v[50:51], v[62:63]
	v_pk_add_f32 v[106:107], v[50:51], v[52:53] op_sel:[1,0] op_sel_hi:[0,1]
	ds_read2_b64 v[50:53], v111 offset0:148 offset1:214
	v_cvt_pk_bf16_f32 v68, v62, v106
	v_add_u32_e32 v107, 0x3c00, v110
	v_mov_b32_e32 v63, v106
	ds_write2_b32 v107, v68, v105 offset0:112 offset1:180
	v_mul_f32_e32 v68, v101, v106
	v_pk_fma_f32 v[108:109], v[100:101], v[62:63], v[68:69] op_sel_hi:[1,1,0] neg_lo:[0,0,1] neg_hi:[0,0,1]
	v_mov_b32_e32 v107, v62
	v_mul_f32_e32 v62, v101, v62
	v_pk_fma_f32 v[62:63], v[100:101], v[106:107], v[62:63] op_sel_hi:[1,1,0]
	s_waitcnt lgkmcnt(1)
	v_pk_add_f32 v[108:109], v[52:53], v[108:109]
	v_pk_add_f32 v[52:53], v[52:53], v[62:63] op_sel:[1,0] op_sel_hi:[0,1]
	v_mov_b32_e32 v109, v52
	v_mul_f32_e32 v62, v101, v52
	v_mov_b32_e32 v53, v108
	v_mul_f32_e32 v68, v101, v108
	v_cvt_pk_bf16_f32 v105, v108, v52
	v_pk_fma_f32 v[62:63], v[100:101], v[108:109], v[62:63] op_sel_hi:[1,1,0] neg_lo:[0,0,1] neg_hi:[0,0,1]
	v_pk_fma_f32 v[52:53], v[100:101], v[52:53], v[68:69] op_sel_hi:[1,1,0]
	v_pk_add_f32 v[62:63], v[50:51], v[62:63]
	v_pk_add_f32 v[106:107], v[50:51], v[52:53] op_sel:[1,0] op_sel_hi:[0,1]
	ds_read2_b64 v[50:53], v111 offset0:16 offset1:82
	v_cvt_pk_bf16_f32 v68, v62, v106
	v_add_u32_e32 v107, 0x3a00, v110
	v_mov_b32_e32 v63, v106
	ds_write2_b32 v107, v68, v105 offset0:104 offset1:172
	v_mul_f32_e32 v68, v101, v106
	v_pk_fma_f32 v[108:109], v[100:101], v[62:63], v[68:69] op_sel_hi:[1,1,0] neg_lo:[0,0,1] neg_hi:[0,0,1]
	v_mov_b32_e32 v107, v62
	v_mul_f32_e32 v62, v101, v62
	v_pk_fma_f32 v[62:63], v[100:101], v[106:107], v[62:63] op_sel_hi:[1,1,0]
	s_waitcnt lgkmcnt(1)
; #define LAS __attribute__((address_space(3)))
; __device__ __forceinline__ unsigned cvtpk(float lo, float hi) { typedef __bf16 bf2 __attribute__((ext_vector_type(2))); f32x2 v = {lo, hi}; bf2 b = __builtin_convertvector(v, bf2); return __builtin_bit_cast(unsigned, b); }
; template <int DIR, bool PASS2>
; __device__ __forceinline__ void s5_sub(LAS unsigned char* ulds, const bf16x8 (&bb)[8], const bf16x8 (&bc)[4], float lbr, float lbi, float& sr, float& si, f32x4& yacc, int sub, int lane) {
;     ...
;     const LAS float* xr = xlds + 2 * lane; LAS unsigned char* sw = slds + lane * 4;
; #pragma unroll
;     for (int q = 0; q < 16; ++q) {
;         const int jj = DIR ? 15 - q : q;
;         const f32x2 x = *(const LAS f32x2*)(xr + jj * S5_XP);
;         const float nr = lbr * sr - lbi * si + x[0], ni = lbr * si + lbi * sr + x[1]; sr = nr; si = ni;
;         if (PASS2) *(LAS unsigned*)(sw + jj * 272) = cvtpk(sr, si);
;     }
;     if (PASS2) {
;         asm volatile("s_waitcnt lgkmcnt(0)" ::: "memory");
;         f32x4 acc = DIR ? yacc : (f32x4){0.f, 0.f, 0.f, 0.f};
;         const LAS unsigned char* sa = slds + hq * 272 + kq * 16;
; #pragma unroll
;         for (int ks = 0; ks < 4; ++ks) { const bf16x8 a = *(const LAS bf16x8*)(sa + ks * 64); acc = __builtin_amdgcn_mfma_f32_16x16x32_bf16(a, bc[ks], acc, 0, 0, 0); }
;         yacc = acc;
	v_pk_add_f32 v[108:109], v[52:53], v[108:109]
	v_pk_add_f32 v[52:53], v[52:53], v[62:63] op_sel:[1,0] op_sel_hi:[0,1]
	v_mov_b32_e32 v109, v52
	v_mul_f32_e32 v62, v101, v52
	v_mov_b32_e32 v53, v108
	v_mul_f32_e32 v68, v101, v108
	v_cvt_pk_bf16_f32 v105, v108, v52
	v_pk_fma_f32 v[62:63], v[100:101], v[108:109], v[62:63] op_sel_hi:[1,1,0] neg_lo:[0,0,1] neg_hi:[0,0,1]
	v_pk_fma_f32 v[52:53], v[100:101], v[52:53], v[68:69] op_sel_hi:[1,1,0]
	v_add_u32_e32 v111, 0x1800, v61
	v_pk_add_f32 v[62:63], v[50:51], v[62:63]
	v_pk_add_f32 v[106:107], v[50:51], v[52:53] op_sel:[1,0] op_sel_hi:[0,1]
	ds_read2_b64 v[50:53], v111 offset0:140 offset1:206
	v_cvt_pk_bf16_f32 v68, v62, v106
	v_add_u32_e32 v107, 0x3800, v110
	v_mov_b32_e32 v63, v106
	ds_write2_b32 v107, v68, v105 offset0:96 offset1:164
	v_mul_f32_e32 v68, v101, v106
	v_pk_fma_f32 v[108:109], v[100:101], v[62:63], v[68:69] op_sel_hi:[1,1,0] neg_lo:[0,0,1] neg_hi:[0,0,1]
	v_mov_b32_e32 v107, v62
	v_mul_f32_e32 v62, v101, v62
	v_pk_fma_f32 v[62:63], v[100:101], v[106:107], v[62:63] op_sel_hi:[1,1,0]
	s_waitcnt lgkmcnt(1)
	v_pk_add_f32 v[108:109], v[52:53], v[108:109]
	v_pk_add_f32 v[52:53], v[52:53], v[62:63] op_sel:[1,0] op_sel_hi:[0,1]
	v_mov_b32_e32 v109, v52
	v_mul_f32_e32 v62, v101, v52
	v_mov_b32_e32 v53, v108
	v_mul_f32_e32 v68, v101, v108
	v_cvt_pk_bf16_f32 v105, v108, v52
	v_pk_fma_f32 v[62:63], v[100:101], v[108:109], v[62:63] op_sel_hi:[1,1,0] neg_lo:[0,0,1] neg_hi:[0,0,1]
	v_pk_fma_f32 v[52:53], v[100:101], v[52:53], v[68:69] op_sel_hi:[1,1,0]
	v_pk_add_f32 v[62:63], v[50:51], v[62:63]
	v_pk_add_f32 v[106:107], v[50:51], v[52:53] op_sel:[1,0] op_sel_hi:[0,1]
	ds_read2_b64 v[50:53], v111 offset0:8 offset1:74
	v_cvt_pk_bf16_f32 v68, v62, v106
	v_add_u32_e32 v107, 0x3600, v110
	v_mov_b32_e32 v63, v106
	ds_write2_b32 v107, v68, v105 offset0:88 offset1:156
	v_mul_f32_e32 v68, v101, v106
	v_pk_fma_f32 v[108:109], v[100:101], v[62:63], v[68:69] op_sel_hi:[1,1,0] neg_lo:[0,0,1] neg_hi:[0,0,1]
	v_mov_b32_e32 v107, v62
	v_mul_f32_e32 v62, v101, v62
	v_pk_fma_f32 v[62:63], v[100:101], v[106:107], v[62:63] op_sel_hi:[1,1,0]
	s_waitcnt lgkmcnt(1)
	v_pk_add_f32 v[108:109], v[52:53], v[108:109]
	v_pk_add_f32 v[52:53], v[52:53], v[62:63] op_sel:[1,0] op_sel_hi:[0,1]
	v_mov_b32_e32 v109, v52
	v_mul_f32_e32 v62, v101, v52
	v_mov_b32_e32 v53, v108
	v_mul_f32_e32 v68, v101, v108
	v_cvt_pk_bf16_f32 v105, v108, v52
	v_pk_fma_f32 v[62:63], v[100:101], v[108:109], v[62:63] op_sel_hi:[1,1,0] neg_lo:[0,0,1] neg_hi:[0,0,1]
	v_pk_fma_f32 v[52:53], v[100:101], v[52:53], v[68:69] op_sel_hi:[1,1,0]
	v_add_u32_e32 v61, 0x1000, v61
	v_pk_add_f32 v[62:63], v[50:51], v[62:63]
	v_pk_add_f32 v[106:107], v[50:51], v[52:53] op_sel:[1,0] op_sel_hi:[0,1]
	ds_read2_b64 v[50:53], v61 offset0:132 offset1:198
	v_cvt_pk_bf16_f32 v68, v62, v106
	v_add_u32_e32 v107, 0x3400, v110
	v_mov_b32_e32 v63, v106
	ds_write2_b32 v107, v68, v105 offset0:80 offset1:148
	v_mul_f32_e32 v68, v101, v106
	v_pk_fma_f32 v[108:109], v[100:101], v[62:63], v[68:69] op_sel_hi:[1,1,0] neg_lo:[0,0,1] neg_hi:[0,0,1]
	v_mov_b32_e32 v107, v62
	v_mul_f32_e32 v62, v101, v62
	v_pk_fma_f32 v[62:63], v[100:101], v[106:107], v[62:63] op_sel_hi:[1,1,0]
	s_waitcnt lgkmcnt(1)
	v_pk_add_f32 v[108:109], v[52:53], v[108:109]
	v_pk_add_f32 v[52:53], v[52:53], v[62:63] op_sel:[1,0] op_sel_hi:[0,1]
	v_mov_b32_e32 v109, v52
	v_mul_f32_e32 v62, v101, v52
	v_mov_b32_e32 v53, v108
	v_mul_f32_e32 v68, v101, v108
	v_cvt_pk_bf16_f32 v105, v108, v52
	v_pk_fma_f32 v[62:63], v[100:101], v[108:109], v[62:63] op_sel_hi:[1,1,0] neg_lo:[0,0,1] neg_hi:[0,0,1]
	v_pk_fma_f32 v[52:53], v[100:101], v[52:53], v[68:69] op_sel_hi:[1,1,0]
	v_pk_add_f32 v[62:63], v[50:51], v[62:63]
	v_pk_add_f32 v[106:107], v[50:51], v[52:53] op_sel:[1,0] op_sel_hi:[0,1]
	v_cvt_pk_bf16_f32 v50, v62, v106
	v_add_u32_e32 v51, 0x3200, v110
	ds_write2_b32 v51, v50, v105 offset0:72 offset1:140
	ds_read2_b64 v[50:53], v61 offset1:66
	v_mov_b32_e32 v63, v106
	v_pk_mul_f32 v[108:109], v[100:101], v[62:63]
	v_mov_b32_e32 v107, v62
	v_mul_f32_e32 v62, v101, v62
	v_pk_fma_f32 v[62:63], v[100:101], v[106:107], v[62:63] op_sel_hi:[1,1,0]
	s_waitcnt lgkmcnt(0)
	v_pk_add_f32 v[62:63], v[52:53], v[62:63] op_sel:[1,0] op_sel_hi:[0,1]
	v_sub_f32_e32 v53, v108, v109
	v_add_f32_e32 v52, v52, v53
	v_cvt_pk_bf16_f32 v61, v52, v62
	v_pk_mul_f32 v[62:63], v[54:55], v[62:63] op_sel_hi:[1,0]
	s_nop 0
	v_pk_fma_f32 v[106:107], v[100:101], v[52:53], v[62:63] op_sel_hi:[1,0,1] neg_lo:[0,0,1] neg_hi:[0,0,1]
	v_pk_fma_f32 v[52:53], v[100:101], v[52:53], v[62:63] op_sel_hi:[1,0,1]
	s_nop 0
	v_mov_b32_e32 v107, v53
	v_pk_add_f32 v[62:63], v[50:51], v[106:107]
	v_add_u32_e32 v51, 0x3000, v110
	v_cvt_pk_bf16_f32 v50, v62, v63
	ds_write2_b32 v51, v50, v61 offset0:64 offset1:132
	s_waitcnt lgkmcnt(0)
	v_add_u32_e32 v61, v112, v113
	ds_read_b128 v[50:53], v61 offset:12544
	ds_read_b128 v[106:109], v61 offset:12608
	s_waitcnt lgkmcnt(1)
	v_mfma_f32_16x16x32_bf16 v[50:53], v[50:53], v[34:37], 0
	ds_read_b128 v[126:129], v61 offset:12672
	s_waitcnt lgkmcnt(1)
	v_mfma_f32_16x16x32_bf16 v[50:53], v[106:109], v[38:41], v[50:53]
	ds_read_b128 v[106:109], v61 offset:12736
	s_waitcnt lgkmcnt(0)
	s_waitcnt vmcnt(3)
	v_lshlrev_b32_e32 v60, 16, v60
	s_waitcnt vmcnt(2)
	v_lshlrev_b32_e32 v61, 16, v58
	s_waitcnt lgkmcnt(1)
	v_mfma_f32_16x16x32_bf16 v[50:53], v[126:129], v[42:45], v[50:53]
	s_waitcnt vmcnt(1)
	v_lshlrev_b32_e32 v58, 16, v59
	s_waitcnt vmcnt(0)
	v_lshlrev_b32_e32 v59, 16, v65
	s_waitcnt lgkmcnt(0)
	v_mfma_f32_16x16x32_bf16 v[50:53], v[106:109], v[46:49], v[50:53]

; #define LAS __attribute__((address_space(3)))
; __device__ __forceinline__ unsigned cvtpk(float lo, float hi) { typedef __bf16 bf2 __attribute__((ext_vector_type(2))); f32x2 v = {lo, hi}; bf2 b = __builtin_convertvector(v, bf2); return __builtin_bit_cast(unsigned, b); }
; template <int DIR, bool PASS2>
; __device__ __forceinline__ void s5_sub(LAS unsigned char* ulds, const bf16x8 (&bb)[8], const bf16x8 (&bc)[4], float lbr, float lbi, float& sr, float& si, f32x4& yacc, int sub, int lane) {
;     ...
;     u32x4 uw = {0u, 0u, 0u, 0u};
;     if (kq < 2) uw = *(const LAS u32x4*)(ulds + (sub * 16 + hq) * 32 + kq * 16);
;     const bf16x8 ua = __builtin_bit_cast(bf16x8, uw);
;     LAS float* xp = xlds + (4 * kq) * S5_XP + hq;
;     f32x4 xs[8];
; #pragma unroll
;     for (int nt = 0; nt < 8; ++nt) xs[nt] = __builtin_amdgcn_mfma_f32_16x16x32_bf16(ua, bb[nt], (f32x4){0.f, 0.f, 0.f, 0.f}, 0, 0, 0);
;     asm volatile("s_nop 15\n\ts_nop 15" : "+v"(xs[0]), "+v"(xs[1]), "+v"(xs[2]), "+v"(xs[3]), "+v"(xs[4]), "+v"(xs[5]), "+v"(xs[6]), "+v"(xs[7]));
; #pragma unroll
;     for (int nt = 0; nt < 8; ++nt) { xp[16 * nt] = xs[nt][0]; xp[16 * nt + S5_XP] = xs[nt][1]; xp[16 * nt + 2 * S5_XP] = xs[nt][2]; xp[16 * nt + 3 * S5_XP] = xs[nt][3]; }
;     asm volatile("s_waitcnt lgkmcnt(0)" ::: "memory");
;     const LAS float* xr = xlds + 2 * lane; LAS unsigned char* sw = slds + lane * 4;
; #pragma unroll
;     for (int q = 0; q < 16; ++q) {
;         const int jj = DIR ? 15 - q : q;
;         const f32x2 x = *(const LAS f32x2*)(xr + jj * S5_XP);
;         const float nr = lbr * sr - lbi * si + x[0], ni = lbr * si + lbi * sr + x[1]; sr = nr; si = ni;
;         if (PASS2) *(LAS unsigned*)(sw + jj * 272) = cvtpk(sr, si);
.LBB0_1927:
	s_and_b64 vcc, exec, s[68:69]
	s_cbranch_vccz .LBB0_1925
	v_mov_b32_e32 v59, 0
	v_mov_b32_e32 v50, 0
	v_mov_b32_e32 v51, 0
	v_mov_b32_e32 v52, 0
	v_mov_b32_e32 v53, 0
	s_and_saveexec_b64 s[68:69], s[8:9]
	ds_read_b128 v[50:53], v104
	s_or_b64 exec, exec, s[68:69]
	s_waitcnt lgkmcnt(0)
	v_mfma_f32_16x16x32_bf16 v[60:63], v[50:53], v[2:5], 0
	v_add_u32_e32 v58, v67, v75
	v_add_u32_e32 v65, 0x1000, v58
	v_add_u32_e32 v58, 0x1400, v58
	v_mfma_f32_16x16x32_bf16 v[106:109], v[50:53], v[6:9], 0
	v_add_u32_e32 v105, s27, v77
	v_mfma_f32_16x16x32_bf16 v[126:129], v[50:53], v[10:13], 0
	v_mfma_f32_16x16x32_bf16 v[130:133], v[50:53], v[14:17], 0
	v_mfma_f32_16x16x32_bf16 v[134:137], v[50:53], v[18:21], 0
	v_mfma_f32_16x16x32_bf16 v[138:141], v[50:53], v[22:25], 0
	v_mfma_f32_16x16x32_bf16 v[142:145], v[50:53], v[26:29], 0
	v_mfma_f32_16x16x32_bf16 v[50:53], v[50:53], v[30:33], 0
	s_nop 3
	s_nop 0
	ds_write2_b32 v65, v60, v106 offset1:16
	ds_write2_b32 v65, v61, v107 offset0:132 offset1:148
	ds_write2_b32 v58, v62, v108 offset0:8 offset1:24
	ds_write2_b32 v58, v63, v109 offset0:140 offset1:156
	ds_write2_b32 v65, v126, v130 offset0:32 offset1:48
	ds_write2_b32 v65, v127, v131 offset0:164 offset1:180
	ds_write2_b32 v58, v128, v132 offset0:40 offset1:56
	ds_write2_b32 v58, v129, v133 offset0:172 offset1:188
	ds_write2_b32 v65, v134, v138 offset0:64 offset1:80
	ds_write2_b32 v65, v135, v139 offset0:196 offset1:212
	ds_write2_b32 v58, v136, v140 offset0:72 offset1:88
	ds_write2_b32 v58, v137, v141 offset0:204 offset1:220
	ds_write2_b32 v65, v142, v50 offset0:96 offset1:112
	ds_write2_b32 v65, v143, v51 offset0:228 offset1:244
	ds_write2_b32 v58, v144, v52 offset0:104 offset1:120
	ds_write2_b32 v58, v145, v53 offset0:236 offset1:252
	v_add_u32_e32 v65, s27, v70
	s_waitcnt lgkmcnt(0)
	v_add_u32_e32 v68, 0x1000, v65
	ds_read2_b64 v[50:53], v68 offset1:66
	v_mul_f32_e32 v58, v101, v103
	v_pk_fma_f32 v[60:61], v[100:101], v[102:103], v[58:59] op_sel_hi:[1,1,0] neg_lo:[0,0,1] neg_hi:[0,0,1]
	v_mul_f32_e32 v58, v55, v103
	v_pk_fma_f32 v[62:63], v[54:55], v[102:103], v[58:59] op_sel_hi:[1,1,0]
	s_waitcnt lgkmcnt(0)
	v_pk_add_f32 v[60:61], v[60:61], v[50:51]
	v_pk_add_f32 v[50:51], v[62:63], v[50:51] op_sel:[0,1] op_sel_hi:[1,0]
	v_add_u32_e32 v106, 0x1800, v65
	v_mov_b32_e32 v61, v50
	v_mul_f32_e32 v58, v101, v50
	v_pk_fma_f32 v[62:63], v[100:101], v[60:61], v[58:59] op_sel_hi:[1,1,0] neg_lo:[0,0,1] neg_hi:[0,0,1]
	v_mov_b32_e32 v51, v60
	v_mul_f32_e32 v58, v101, v60
	v_cvt_pk_bf16_f32 v102, v60, v50
	v_pk_fma_f32 v[50:51], v[100:101], v[50:51], v[58:59] op_sel_hi:[1,1,0]
	v_pk_add_f32 v[62:63], v[52:53], v[62:63]
	v_pk_add_f32 v[60:61], v[52:53], v[50:51] op_sel:[1,0] op_sel_hi:[0,1]
	ds_read2_b64 v[50:53], v68 offset0:132 offset1:198
	v_cvt_pk_bf16_f32 v58, v62, v60
	v_add_u32_e32 v61, 0x3000, v105
	v_mov_b32_e32 v63, v60
	ds_write2_b32 v61, v102, v58 offset0:64 offset1:132
	v_mul_f32_e32 v58, v101, v60
	v_pk_fma_f32 v[102:103], v[100:101], v[62:63], v[58:59] op_sel_hi:[1,1,0] neg_lo:[0,0,1] neg_hi:[0,0,1]
	v_mov_b32_e32 v61, v62
	v_mul_f32_e32 v58, v101, v62
	v_pk_fma_f32 v[60:61], v[100:101], v[60:61], v[58:59] op_sel_hi:[1,1,0]
	s_waitcnt lgkmcnt(1)
	v_pk_add_f32 v[102:103], v[50:51], v[102:103]
	v_pk_add_f32 v[50:51], v[50:51], v[60:61] op_sel:[1,0] op_sel_hi:[0,1]
	v_mov_b32_e32 v103, v50
	v_mul_f32_e32 v58, v101, v50
	v_pk_fma_f32 v[60:61], v[100:101], v[102:103], v[58:59] op_sel_hi:[1,1,0] neg_lo:[0,0,1] neg_hi:[0,0,1]
	v_mov_b32_e32 v51, v102
	v_mul_f32_e32 v58, v101, v102
	v_cvt_pk_bf16_f32 v68, v102, v50
	v_pk_fma_f32 v[50:51], v[100:101], v[50:51], v[58:59] op_sel_hi:[1,1,0]
	v_pk_add_f32 v[60:61], v[52:53], v[60:61]
	v_pk_add_f32 v[62:63], v[52:53], v[50:51] op_sel:[1,0] op_sel_hi:[0,1]
	ds_read2_b64 v[50:53], v106 offset0:8 offset1:74
	v_cvt_pk_bf16_f32 v58, v60, v62
	v_add_u32_e32 v63, 0x3200, v105
	v_mov_b32_e32 v61, v62
	ds_write2_b32 v63, v68, v58 offset0:72 offset1:140
	v_mul_f32_e32 v58, v101, v62
	v_pk_fma_f32 v[102:103], v[100:101], v[60:61], v[58:59] op_sel_hi:[1,1,0] neg_lo:[0,0,1] neg_hi:[0,0,1]
	v_mov_b32_e32 v63, v60
	v_mul_f32_e32 v58, v101, v60
	v_pk_fma_f32 v[60:61], v[100:101], v[62:63], v[58:59] op_sel_hi:[1,1,0]
	s_waitcnt lgkmcnt(1)
	v_pk_add_f32 v[102:103], v[50:51], v[102:103]
	v_pk_add_f32 v[50:51], v[50:51], v[60:61] op_sel:[1,0] op_sel_hi:[0,1]
	v_mov_b32_e32 v103, v50
	v_mul_f32_e32 v58, v101, v50
	v_pk_fma_f32 v[60:61], v[100:101], v[102:103], v[58:59] op_sel_hi:[1,1,0] neg_lo:[0,0,1] neg_hi:[0,0,1]
	v_mov_b32_e32 v51, v102
	v_mul_f32_e32 v58, v101, v102
	v_cvt_pk_bf16_f32 v68, v102, v50
	v_pk_fma_f32 v[50:51], v[100:101], v[50:51], v[58:59] op_sel_hi:[1,1,0]
	v_pk_add_f32 v[60:61], v[52:53], v[60:61]
	v_pk_add_f32 v[62:63], v[52:53], v[50:51] op_sel:[1,0] op_sel_hi:[0,1]
	ds_read2_b64 v[50:53], v106 offset0:140 offset1:206
	v_cvt_pk_bf16_f32 v58, v60, v62
	v_add_u32_e32 v63, 0x3400, v105
	v_mov_b32_e32 v61, v62
	ds_write2_b32 v63, v68, v58 offset0:80 offset1:148
	v_mul_f32_e32 v58, v101, v62
	v_pk_fma_f32 v[102:103], v[100:101], v[60:61], v[58:59] op_sel_hi:[1,1,0] neg_lo:[0,0,1] neg_hi:[0,0,1]
	v_mov_b32_e32 v63, v60
	v_mul_f32_e32 v58, v101, v60
	v_pk_fma_f32 v[60:61], v[100:101], v[62:63], v[58:59] op_sel_hi:[1,1,0]
	s_waitcnt lgkmcnt(1)
; #define LAS __attribute__((address_space(3)))
; __device__ __forceinline__ unsigned cvtpk(float lo, float hi) { typedef __bf16 bf2 __attribute__((ext_vector_type(2))); f32x2 v = {lo, hi}; bf2 b = __builtin_convertvector(v, bf2); return __builtin_bit_cast(unsigned, b); }
; template <int DIR, bool PASS2>
; __device__ __forceinline__ void s5_sub(LAS unsigned char* ulds, const bf16x8 (&bb)[8], const bf16x8 (&bc)[4], float lbr, float lbi, float& sr, float& si, f32x4& yacc, int sub, int lane) {
;     ...
;     const LAS float* xr = xlds + 2 * lane; LAS unsigned char* sw = slds + lane * 4;
; #pragma unroll
;     for (int q = 0; q < 16; ++q) {
;         const int jj = DIR ? 15 - q : q;
;         const f32x2 x = *(const LAS f32x2*)(xr + jj * S5_XP);
;         const float nr = lbr * sr - lbi * si + x[0], ni = lbr * si + lbi * sr + x[1]; sr = nr; si = ni;
;         if (PASS2) *(LAS unsigned*)(sw + jj * 272) = cvtpk(sr, si);
;     }
;     if (PASS2) {
;         asm volatile("s_waitcnt lgkmcnt(0)" ::: "memory");
;         f32x4 acc = DIR ? yacc : (f32x4){0.f, 0.f, 0.f, 0.f};
;         const LAS unsigned char* sa = slds + hq * 272 + kq * 16;
; #pragma unroll
;         for (int ks = 0; ks < 4; ++ks) { const bf16x8 a = *(const LAS bf16x8*)(sa + ks * 64); acc = __builtin_amdgcn_mfma_f32_16x16x32_bf16(a, bc[ks], acc, 0, 0, 0); }
;         yacc = acc;
	v_pk_add_f32 v[102:103], v[50:51], v[102:103]
	v_pk_add_f32 v[50:51], v[50:51], v[60:61] op_sel:[1,0] op_sel_hi:[0,1]
	v_mov_b32_e32 v103, v50
	v_mul_f32_e32 v58, v101, v50
	v_pk_fma_f32 v[60:61], v[100:101], v[102:103], v[58:59] op_sel_hi:[1,1,0] neg_lo:[0,0,1] neg_hi:[0,0,1]
	v_mov_b32_e32 v51, v102
	v_mul_f32_e32 v58, v101, v102
	v_cvt_pk_bf16_f32 v68, v102, v50
	v_pk_fma_f32 v[50:51], v[100:101], v[50:51], v[58:59] op_sel_hi:[1,1,0]
	v_add_u32_e32 v106, 0x2000, v65
	v_pk_add_f32 v[60:61], v[52:53], v[60:61]
	v_pk_add_f32 v[62:63], v[52:53], v[50:51] op_sel:[1,0] op_sel_hi:[0,1]
	ds_read2_b64 v[50:53], v106 offset0:16 offset1:82
	v_cvt_pk_bf16_f32 v58, v60, v62
	v_add_u32_e32 v63, 0x3600, v105
	v_mov_b32_e32 v61, v62
	ds_write2_b32 v63, v68, v58 offset0:88 offset1:156
	v_mul_f32_e32 v58, v101, v62
	v_pk_fma_f32 v[102:103], v[100:101], v[60:61], v[58:59] op_sel_hi:[1,1,0] neg_lo:[0,0,1] neg_hi:[0,0,1]
	v_mov_b32_e32 v63, v60
	v_mul_f32_e32 v58, v101, v60
	v_pk_fma_f32 v[60:61], v[100:101], v[62:63], v[58:59] op_sel_hi:[1,1,0]
	s_waitcnt lgkmcnt(1)
	v_pk_add_f32 v[102:103], v[50:51], v[102:103]
	v_pk_add_f32 v[50:51], v[50:51], v[60:61] op_sel:[1,0] op_sel_hi:[0,1]
	v_mov_b32_e32 v103, v50
	v_mul_f32_e32 v58, v101, v50
	v_pk_fma_f32 v[60:61], v[100:101], v[102:103], v[58:59] op_sel_hi:[1,1,0] neg_lo:[0,0,1] neg_hi:[0,0,1]
	v_mov_b32_e32 v51, v102
	v_mul_f32_e32 v58, v101, v102
	v_cvt_pk_bf16_f32 v68, v102, v50
	v_pk_fma_f32 v[50:51], v[100:101], v[50:51], v[58:59] op_sel_hi:[1,1,0]
	v_pk_add_f32 v[60:61], v[52:53], v[60:61]
	v_pk_add_f32 v[62:63], v[52:53], v[50:51] op_sel:[1,0] op_sel_hi:[0,1]
	ds_read2_b64 v[50:53], v106 offset0:148 offset1:214
	v_cvt_pk_bf16_f32 v58, v60, v62
	v_add_u32_e32 v63, 0x3800, v105
	v_mov_b32_e32 v61, v62
	ds_write2_b32 v63, v68, v58 offset0:96 offset1:164
	v_mul_f32_e32 v58, v101, v62
	v_pk_fma_f32 v[102:103], v[100:101], v[60:61], v[58:59] op_sel_hi:[1,1,0] neg_lo:[0,0,1] neg_hi:[0,0,1]
	v_mov_b32_e32 v63, v60
	v_mul_f32_e32 v58, v101, v60
	v_pk_fma_f32 v[60:61], v[100:101], v[62:63], v[58:59] op_sel_hi:[1,1,0]
	s_waitcnt lgkmcnt(1)
	v_pk_add_f32 v[102:103], v[50:51], v[102:103]
	v_pk_add_f32 v[50:51], v[50:51], v[60:61] op_sel:[1,0] op_sel_hi:[0,1]
	v_mov_b32_e32 v103, v50
	v_mul_f32_e32 v58, v101, v50
	v_pk_fma_f32 v[60:61], v[100:101], v[102:103], v[58:59] op_sel_hi:[1,1,0] neg_lo:[0,0,1] neg_hi:[0,0,1]
	v_mov_b32_e32 v51, v102
	v_mul_f32_e32 v58, v101, v102
	v_cvt_pk_bf16_f32 v68, v102, v50
	v_pk_fma_f32 v[50:51], v[100:101], v[50:51], v[58:59] op_sel_hi:[1,1,0]
	v_add_u32_e32 v65, 0x2800, v65
	v_pk_add_f32 v[60:61], v[52:53], v[60:61]
	v_pk_add_f32 v[62:63], v[52:53], v[50:51] op_sel:[1,0] op_sel_hi:[0,1]
	ds_read2_b64 v[50:53], v65 offset0:24 offset1:90
	v_cvt_pk_bf16_f32 v58, v60, v62
	v_add_u32_e32 v63, 0x3a00, v105
	v_mov_b32_e32 v61, v62
	ds_write2_b32 v63, v68, v58 offset0:104 offset1:172
	v_mul_f32_e32 v58, v101, v62
	v_pk_fma_f32 v[102:103], v[100:101], v[60:61], v[58:59] op_sel_hi:[1,1,0] neg_lo:[0,0,1] neg_hi:[0,0,1]
	v_mov_b32_e32 v63, v60
	v_mul_f32_e32 v58, v101, v60
	v_pk_fma_f32 v[60:61], v[100:101], v[62:63], v[58:59] op_sel_hi:[1,1,0]
	s_waitcnt lgkmcnt(1)
	v_pk_add_f32 v[102:103], v[50:51], v[102:103]
	v_pk_add_f32 v[50:51], v[50:51], v[60:61] op_sel:[1,0] op_sel_hi:[0,1]
	v_mov_b32_e32 v103, v50
	v_mul_f32_e32 v58, v101, v50
	v_pk_fma_f32 v[60:61], v[100:101], v[102:103], v[58:59] op_sel_hi:[1,1,0] neg_lo:[0,0,1] neg_hi:[0,0,1]
	v_mov_b32_e32 v51, v102
	v_mul_f32_e32 v58, v101, v102
	v_cvt_pk_bf16_f32 v68, v102, v50
	v_pk_fma_f32 v[50:51], v[100:101], v[50:51], v[58:59] op_sel_hi:[1,1,0]
	v_pk_add_f32 v[60:61], v[52:53], v[60:61]
	v_pk_add_f32 v[62:63], v[52:53], v[50:51] op_sel:[1,0] op_sel_hi:[0,1]
	v_cvt_pk_bf16_f32 v50, v60, v62
	v_add_u32_e32 v51, 0x3c00, v105
	ds_write2_b32 v51, v68, v50 offset0:112 offset1:180
	ds_read2_b64 v[50:53], v65 offset0:156 offset1:222
	v_mov_b32_e32 v61, v62
	v_mov_b32_e32 v63, v60
	v_mul_f32_e32 v58, v101, v60
	v_pk_mul_f32 v[102:103], v[100:101], v[60:61]
	v_pk_fma_f32 v[60:61], v[100:101], v[62:63], v[58:59] op_sel_hi:[1,1,0]
	s_waitcnt lgkmcnt(0)
	v_pk_add_f32 v[60:61], v[50:51], v[60:61] op_sel:[1,0] op_sel_hi:[0,1]
	v_sub_f32_e32 v51, v102, v103
	v_add_f32_e32 v50, v50, v51
	v_cvt_pk_bf16_f32 v58, v50, v60
	v_pk_mul_f32 v[60:61], v[54:55], v[60:61] op_sel_hi:[1,0]
	s_nop 0
	v_pk_fma_f32 v[62:63], v[100:101], v[50:51], v[60:61] op_sel_hi:[1,0,1] neg_lo:[0,0,1] neg_hi:[0,0,1]
	v_pk_fma_f32 v[50:51], v[100:101], v[50:51], v[60:61] op_sel_hi:[1,0,1]
	s_nop 0
	v_mov_b32_e32 v63, v51
	v_pk_add_f32 v[62:63], v[52:53], v[62:63]
	v_add_u32_e32 v51, 0x3e00, v105
	v_cvt_pk_bf16_f32 v50, v62, v63
	ds_write2_b32 v51, v58, v50 offset0:120 offset1:188
	s_waitcnt lgkmcnt(0)
	v_add_u32_e32 v58, v112, v113
	ds_read_b128 v[50:53], v58 offset:12544
	ds_read_b128 v[106:109], v58 offset:12608
	s_waitcnt lgkmcnt(1)
	v_mfma_f32_16x16x32_bf16 v[50:53], v[50:53], v[34:37], 0
	ds_read_b128 v[126:129], v58 offset:12672
	s_waitcnt lgkmcnt(1)
	v_mfma_f32_16x16x32_bf16 v[50:53], v[106:109], v[38:41], v[50:53]
	ds_read_b128 v[106:109], v58 offset:12736
	s_waitcnt lgkmcnt(0)
	s_waitcnt lgkmcnt(1)
	v_mfma_f32_16x16x32_bf16 v[50:53], v[126:129], v[42:45], v[50:53]
	s_waitcnt lgkmcnt(0)
	v_mfma_f32_16x16x32_bf16 v[50:53], v[106:109], v[46:49], v[50:53]
	v_mov_b32_e32 v58, 0
	v_mov_b32_e32 v61, 0
	v_mov_b32_e32 v60, 0
	v_mov_b64_e32 v[102:103], v[62:63]
	s_and_b64 vcc, exec, s[10:11]
	s_mov_b64 s[10:11], -1
	s_cbranch_vccz .LBB0_1926
